# back-edge rotation (7.11): K-loop counter/pointer SALU moved in front of the loop-closing barrier in 6 GEMM loops, on top of noprio+nonop
# baseline (speedup 1.0000x reference)
; #define PG8_STAGE(bufoff, gbase, voff) do { _Pragma("unroll") for (int _i = 0; _i < 2; ++_i) \
;         __builtin_amdgcn_global_load_lds((const unsigned*)((const char*)(gbase) + (voff)[_i]), (LAS unsigned*)(lds + (bufoff) + ldsw + _i * 8192), 16, 0, 0); } while (0)
; #define PG8_LDA(dst, b, h) do { _Pragma("unroll") for (int m = 0; m < 4; ++m) _Pragma("unroll") for (int k = 0; k < 2; ++k) dst[m][k] = *(const LAS bf16x8*)(lds + PG8_SA(b, h) + aoff + m * 2048 + k * 1024); } while (0)
; #define PG8_LDB(dst, b, h) do { _Pragma("unroll") for (int n = 0; n < 2; ++n) _Pragma("unroll") for (int k = 0; k < 2; ++k) dst[n][k] = *(const LAS bf16x8*)(lds + PG8_SB(b, h) + boff + n * 2048 + k * 1024); } while (0)
; #define PG8_MMA(ai, bj, At, Bt) do { __builtin_amdgcn_s_setprio(1); _Pragma("unroll") for (int m = 0; m < 4; ++m) _Pragma("unroll") for (int n = 0; n < 2; ++n) _Pragma("unroll") for (int k = 0; k < 2; ++k) \
;         acc[ai][bj][m][n] = __builtin_amdgcn_mfma_f32_16x16x32_bf16(Bt[n][k], At[m][k], acc[ai][bj][m][n], 0, 0, 0); __builtin_amdgcn_s_setprio(0); } while (0)
; #define PG8_WAIT_V(n) asm volatile("s_waitcnt vmcnt(" #n ")" ::: "memory")
; #define PG8_WAIT_L(n) asm volatile("s_waitcnt lgkmcnt(" #n ")" ::: "memory")
; #define PG8_BAR __builtin_amdgcn_s_barrier()
; #define PG8_SCHED __builtin_amdgcn_sched_barrier(0)
; template <class Epi, class Sched, bool ALIGN_EPI = true>
; __device__ __forceinline__ void gemm_phase(LAS unsigned char* lds, const Gemm g, const Sched& S, const Epi& E) {
;     ...
;             PG8_LDB(B0, 0, 0); PG8_LDB(B1, 0, 1); PG8_SCHED; PG8_LDA(At, 0, 0); PG8_STAGE(PG8_SA(1, 1), a1 + hstep, voffA);
;             PG8_WAIT_V(8); PG8_WAIT_L(0); PG8_BAR; PG8_MMA(0, 0, At, B0); PG8_MMA(0, 1, At, B1); PG8_BAR; PG8_SCHED;
;             PG8_LDA(At, 0, 1); PG8_STAGE(PG8_SB(0, 0), b2, voffB); PG8_STAGE(PG8_SB(0, 1), b2 + hstep, voffB); PG8_STAGE(PG8_SA(0, 0), a2, voffA);
;             PG8_WAIT_V(8); PG8_WAIT_L(0); PG8_BAR; PG8_MMA(1, 0, At, B0); PG8_MMA(1, 1, At, B1); PG8_BAR; PG8_SCHED;
.LBB0_195:
	v_add_u32_e32 v136, s78, v169
	ds_read_b128 v[172:175], v136
	ds_read_b128 v[180:183], v136 offset:1024
	ds_read_b128 v[184:187], v136 offset:2048
	ds_read_b128 v[188:191], v136 offset:3072
	v_add_u32_e32 v136, s79, v169
	ds_read_b128 v[192:195], v136
	ds_read_b128 v[196:199], v136 offset:1024
	ds_read_b128 v[204:207], v136 offset:2048
	ds_read_b128 v[208:211], v136 offset:3072
	s_add_u32 s36, s34, 0xfff80080
	s_addc_u32 s37, s35, -1
	s_cmp_eq_u32 s89, 28
	s_cselect_b32 s39, s84, s37
	s_cselect_b32 s38, s85, s36
	s_cselect_b32 s37, s9, s88
	s_cselect_b32 s36, s86, s87
	v_lshl_add_u64 v[164:165], s[34:35], 0, v[160:161]
	s_add_i32 m0, s44, 0xc000
	ds_read_b128 v[212:215], v171
	ds_read_b128 v[216:219], v171 offset:1024
	ds_read_b128 v[220:223], v171 offset:2048
	ds_read_b128 v[224:227], v171 offset:3072
	ds_read_b128 v[228:231], v171 offset:4096
	ds_read_b128 v[232:235], v171 offset:5120
	ds_read_b128 v[236:239], v171 offset:6144
	ds_read_b128 v[240:243], v171 offset:7168
	global_load_lds_dwordx4 v[164:165], off
	s_add_i32 m0, s44, 0xe000
	v_lshl_add_u64 v[164:165], s[34:35], 0, v[162:163]
	global_load_lds_dwordx4 v[164:165], off
	s_waitcnt vmcnt(8)
	s_waitcnt lgkmcnt(0)
	s_barrier
	s_waitcnt lgkmcnt(0)
	v_mfma_f32_16x16x32_bf16 v[124:127], v[172:175], v[212:215], v[124:127]
	v_mfma_f32_16x16x32_bf16 v[120:123], v[184:187], v[212:215], v[120:123]
	v_mfma_f32_16x16x32_bf16 v[108:111], v[172:175], v[220:223], v[108:111]
	v_mfma_f32_16x16x32_bf16 v[104:107], v[184:187], v[220:223], v[104:107]
	v_mfma_f32_16x16x32_bf16 v[92:95], v[172:175], v[228:231], v[92:95]
	v_mfma_f32_16x16x32_bf16 v[88:91], v[184:187], v[228:231], v[88:91]
	v_mfma_f32_16x16x32_bf16 v[76:79], v[172:175], v[236:239], v[76:79]
	v_mfma_f32_16x16x32_bf16 v[72:75], v[184:187], v[236:239], v[72:75]
	v_mfma_f32_16x16x32_bf16 v[124:127], v[180:183], v[216:219], v[124:127]
	v_mfma_f32_16x16x32_bf16 v[120:123], v[188:191], v[216:219], v[120:123]
	v_mfma_f32_16x16x32_bf16 v[108:111], v[180:183], v[224:227], v[108:111]
	v_mfma_f32_16x16x32_bf16 v[104:107], v[188:191], v[224:227], v[104:107]
	v_mfma_f32_16x16x32_bf16 v[92:95], v[180:183], v[232:235], v[92:95]
	v_mfma_f32_16x16x32_bf16 v[88:91], v[188:191], v[232:235], v[88:91]
	v_mfma_f32_16x16x32_bf16 v[76:79], v[180:183], v[240:243], v[76:79]
	v_mfma_f32_16x16x32_bf16 v[72:75], v[188:191], v[240:243], v[72:75]
	v_mfma_f32_16x16x32_bf16 v[116:119], v[192:195], v[212:215], v[116:119]
	v_mfma_f32_16x16x32_bf16 v[112:115], v[204:207], v[212:215], v[112:115]
	v_mfma_f32_16x16x32_bf16 v[100:103], v[192:195], v[220:223], v[100:103]
	v_mfma_f32_16x16x32_bf16 v[96:99], v[204:207], v[220:223], v[96:99]
	v_mfma_f32_16x16x32_bf16 v[84:87], v[192:195], v[228:231], v[84:87]
	v_mfma_f32_16x16x32_bf16 v[80:83], v[204:207], v[228:231], v[80:83]
	v_mfma_f32_16x16x32_bf16 v[68:71], v[192:195], v[236:239], v[68:71]
	v_mfma_f32_16x16x32_bf16 v[64:67], v[204:207], v[236:239], v[64:67]
	v_mfma_f32_16x16x32_bf16 v[116:119], v[196:199], v[216:219], v[116:119]
	v_mfma_f32_16x16x32_bf16 v[112:115], v[208:211], v[216:219], v[112:115]
	v_mfma_f32_16x16x32_bf16 v[100:103], v[196:199], v[224:227], v[100:103]
	v_mfma_f32_16x16x32_bf16 v[96:99], v[208:211], v[224:227], v[96:99]
	v_mfma_f32_16x16x32_bf16 v[84:87], v[196:199], v[232:235], v[84:87]
	v_mfma_f32_16x16x32_bf16 v[80:83], v[208:211], v[232:235], v[80:83]
	v_mfma_f32_16x16x32_bf16 v[68:71], v[196:199], v[240:243], v[68:71]
	v_mfma_f32_16x16x32_bf16 v[64:67], v[208:211], v[240:243], v[64:67]
	s_barrier
	s_add_i32 s46, s78, s42
	v_lshl_add_u64 v[164:165], s[36:37], 0, v[130:131]
	s_mov_b32 m0, s46
	ds_read_b128 v[212:215], v171 offset:16384
	ds_read_b128 v[216:219], v171 offset:17408
	ds_read_b128 v[220:223], v171 offset:18432
	ds_read_b128 v[224:227], v171 offset:19456
	ds_read_b128 v[228:231], v171 offset:20480
	ds_read_b128 v[232:235], v171 offset:21504
	ds_read_b128 v[236:239], v171 offset:22528
	ds_read_b128 v[240:243], v171 offset:23552
	global_load_lds_dwordx4 v[164:165], off
	s_add_i32 m0, s46, 0x2000
	s_add_u32 s90, s36, 0x80000
	v_lshl_add_u64 v[176:177], s[36:37], 0, v[134:135]
	s_addc_u32 s91, s37, 0
	s_add_i32 s46, s79, s42
	global_load_lds_dwordx4 v[176:177], off
	v_lshl_add_u64 v[200:201], s[90:91], 0, v[130:131]
	s_mov_b32 m0, s46
	v_lshl_add_u64 v[244:245], s[38:39], 0, v[132:133]
	global_load_lds_dwordx4 v[200:201], off
	s_add_i32 m0, s46, 0x2000
	v_lshl_add_u64 v[200:201], s[90:91], 0, v[134:135]
	global_load_lds_dwordx4 v[200:201], off
	s_mov_b32 m0, s44
	v_lshl_add_u64 v[200:201], s[38:39], 0, v[128:129]
	global_load_lds_dwordx4 v[200:201], off
	s_mov_b32 m0, s50
	s_nop 0
	global_load_lds_dwordx4 v[244:245], off
	s_waitcnt vmcnt(8)
	s_waitcnt lgkmcnt(0)
	s_barrier
; #define PG8_STAGE(bufoff, gbase, voff) do { _Pragma("unroll") for (int _i = 0; _i < 2; ++_i) \
;         __builtin_amdgcn_global_load_lds((const unsigned*)((const char*)(gbase) + (voff)[_i]), (LAS unsigned*)(lds + (bufoff) + ldsw + _i * 8192), 16, 0, 0); } while (0)
; #define PG8_LDA(dst, b, h) do { _Pragma("unroll") for (int m = 0; m < 4; ++m) _Pragma("unroll") for (int k = 0; k < 2; ++k) dst[m][k] = *(const LAS bf16x8*)(lds + PG8_SA(b, h) + aoff + m * 2048 + k * 1024); } while (0)
; #define PG8_LDB(dst, b, h) do { _Pragma("unroll") for (int n = 0; n < 2; ++n) _Pragma("unroll") for (int k = 0; k < 2; ++k) dst[n][k] = *(const LAS bf16x8*)(lds + PG8_SB(b, h) + boff + n * 2048 + k * 1024); } while (0)
; #define PG8_MMA(ai, bj, At, Bt) do { __builtin_amdgcn_s_setprio(1); _Pragma("unroll") for (int m = 0; m < 4; ++m) _Pragma("unroll") for (int n = 0; n < 2; ++n) _Pragma("unroll") for (int k = 0; k < 2; ++k) \
;         acc[ai][bj][m][n] = __builtin_amdgcn_mfma_f32_16x16x32_bf16(Bt[n][k], At[m][k], acc[ai][bj][m][n], 0, 0, 0); __builtin_amdgcn_s_setprio(0); } while (0)
; #define PG8_WAIT_V(n) asm volatile("s_waitcnt vmcnt(" #n ")" ::: "memory")
; #define PG8_WAIT_L(n) asm volatile("s_waitcnt lgkmcnt(" #n ")" ::: "memory")
; #define PG8_BAR __builtin_amdgcn_s_barrier()
; #define PG8_SCHED __builtin_amdgcn_sched_barrier(0)
; template <class Epi, class Sched, bool ALIGN_EPI = true>
; __device__ __forceinline__ void gemm_phase(LAS unsigned char* lds, const Gemm g, const Sched& S, const Epi& E) {
;     ...
;             PG8_WAIT_V(8); PG8_WAIT_L(0); PG8_BAR; PG8_MMA(1, 0, At, B0); PG8_MMA(1, 1, At, B1); PG8_BAR; PG8_SCHED;
;             PG8_LDB(B0, 1, 0); PG8_LDB(B1, 1, 1); PG8_SCHED; PG8_LDA(At, 1, 0); PG8_STAGE(PG8_SA(0, 1), a2 + hstep, voffA);
;             PG8_WAIT_V(8); PG8_WAIT_L(0); PG8_BAR; PG8_MMA(0, 0, At, B0); PG8_MMA(0, 1, At, B1); PG8_BAR; PG8_SCHED;
	s_waitcnt lgkmcnt(0)
	v_mfma_f32_16x16x32_bf16 v[60:63], v[172:175], v[212:215], v[60:63]
	v_mfma_f32_16x16x32_bf16 v[56:59], v[184:187], v[212:215], v[56:59]
	v_mfma_f32_16x16x32_bf16 v[44:47], v[172:175], v[220:223], v[44:47]
	v_mfma_f32_16x16x32_bf16 v[40:43], v[184:187], v[220:223], v[40:43]
	v_mfma_f32_16x16x32_bf16 v[28:31], v[172:175], v[228:231], v[28:31]
	v_mfma_f32_16x16x32_bf16 v[24:27], v[184:187], v[228:231], v[24:27]
	v_mfma_f32_16x16x32_bf16 v[12:15], v[172:175], v[236:239], v[12:15]
	v_mfma_f32_16x16x32_bf16 v[8:11], v[184:187], v[236:239], v[8:11]
	v_mfma_f32_16x16x32_bf16 v[60:63], v[180:183], v[216:219], v[60:63]
	v_mfma_f32_16x16x32_bf16 v[56:59], v[188:191], v[216:219], v[56:59]
	v_mfma_f32_16x16x32_bf16 v[44:47], v[180:183], v[224:227], v[44:47]
	v_mfma_f32_16x16x32_bf16 v[40:43], v[188:191], v[224:227], v[40:43]
	v_mfma_f32_16x16x32_bf16 v[28:31], v[180:183], v[232:235], v[28:31]
	v_mfma_f32_16x16x32_bf16 v[24:27], v[188:191], v[232:235], v[24:27]
	v_mfma_f32_16x16x32_bf16 v[12:15], v[180:183], v[240:243], v[12:15]
	v_mfma_f32_16x16x32_bf16 v[8:11], v[188:191], v[240:243], v[8:11]
	v_mfma_f32_16x16x32_bf16 v[52:55], v[192:195], v[212:215], v[52:55]
	v_mfma_f32_16x16x32_bf16 v[48:51], v[204:207], v[212:215], v[48:51]
	v_mfma_f32_16x16x32_bf16 v[36:39], v[192:195], v[220:223], v[36:39]
	v_mfma_f32_16x16x32_bf16 v[32:35], v[204:207], v[220:223], v[32:35]
	v_mfma_f32_16x16x32_bf16 v[20:23], v[192:195], v[228:231], v[20:23]
	v_mfma_f32_16x16x32_bf16 v[16:19], v[204:207], v[228:231], v[16:19]
	v_mfma_f32_16x16x32_bf16 v[4:7], v[192:195], v[236:239], v[4:7]
	v_mfma_f32_16x16x32_bf16 v[0:3], v[204:207], v[236:239], v[0:3]
	v_mfma_f32_16x16x32_bf16 v[52:55], v[196:199], v[216:219], v[52:55]
	v_mfma_f32_16x16x32_bf16 v[48:51], v[208:211], v[216:219], v[48:51]
	v_mfma_f32_16x16x32_bf16 v[36:39], v[196:199], v[224:227], v[36:39]
	v_mfma_f32_16x16x32_bf16 v[32:35], v[208:211], v[224:227], v[32:35]
	v_mfma_f32_16x16x32_bf16 v[20:23], v[196:199], v[232:235], v[20:23]
	v_mfma_f32_16x16x32_bf16 v[16:19], v[208:211], v[232:235], v[16:19]
	v_mfma_f32_16x16x32_bf16 v[4:7], v[196:199], v[240:243], v[4:7]
	v_mfma_f32_16x16x32_bf16 v[0:3], v[208:211], v[240:243], v[0:3]
	s_barrier
	s_add_i32 s46, 0, 0x18000
	v_add_u32_e32 v136, s46, v169
	s_add_i32 s47, 0, 0x1c000
	ds_read_b128 v[172:175], v136
	ds_read_b128 v[180:183], v136 offset:1024
	ds_read_b128 v[184:187], v136 offset:2048
	ds_read_b128 v[188:191], v136 offset:3072
	v_add_u32_e32 v136, s47, v169
	ds_read_b128 v[192:195], v136
	ds_read_b128 v[196:199], v136 offset:1024
	ds_read_b128 v[204:207], v136 offset:2048
	ds_read_b128 v[208:211], v136 offset:3072
	s_add_u32 s38, s38, 0x80000
	s_addc_u32 s39, s39, 0
	s_mov_b32 m0, s52
	v_lshl_add_u64 v[246:247], s[38:39], 0, v[128:129]
	ds_read_b128 v[212:215], v171 offset:32768
	ds_read_b128 v[216:219], v171 offset:33792
	ds_read_b128 v[220:223], v171 offset:34816
	ds_read_b128 v[224:227], v171 offset:35840
	ds_read_b128 v[228:231], v171 offset:36864
	ds_read_b128 v[232:235], v171 offset:37888
	ds_read_b128 v[236:239], v171 offset:38912
	ds_read_b128 v[240:243], v171 offset:39936
	global_load_lds_dwordx4 v[246:247], off
	s_mov_b32 m0, s53
	v_lshl_add_u64 v[246:247], s[38:39], 0, v[132:133]
	global_load_lds_dwordx4 v[246:247], off
	s_waitcnt vmcnt(8)
	s_waitcnt lgkmcnt(0)
	s_barrier
	s_waitcnt lgkmcnt(0)
	v_mfma_f32_16x16x32_bf16 v[124:127], v[172:175], v[212:215], v[124:127]
	v_mfma_f32_16x16x32_bf16 v[120:123], v[184:187], v[212:215], v[120:123]
	v_mfma_f32_16x16x32_bf16 v[108:111], v[172:175], v[220:223], v[108:111]
	v_mfma_f32_16x16x32_bf16 v[104:107], v[184:187], v[220:223], v[104:107]
	v_mfma_f32_16x16x32_bf16 v[92:95], v[172:175], v[228:231], v[92:95]
	v_mfma_f32_16x16x32_bf16 v[88:91], v[184:187], v[228:231], v[88:91]
	v_mfma_f32_16x16x32_bf16 v[76:79], v[172:175], v[236:239], v[76:79]
	v_mfma_f32_16x16x32_bf16 v[72:75], v[184:187], v[236:239], v[72:75]
	v_mfma_f32_16x16x32_bf16 v[124:127], v[180:183], v[216:219], v[124:127]
	v_mfma_f32_16x16x32_bf16 v[120:123], v[188:191], v[216:219], v[120:123]
	v_mfma_f32_16x16x32_bf16 v[108:111], v[180:183], v[224:227], v[108:111]
	v_mfma_f32_16x16x32_bf16 v[104:107], v[188:191], v[224:227], v[104:107]
	v_mfma_f32_16x16x32_bf16 v[92:95], v[180:183], v[232:235], v[92:95]
	v_mfma_f32_16x16x32_bf16 v[88:91], v[188:191], v[232:235], v[88:91]
	v_mfma_f32_16x16x32_bf16 v[76:79], v[180:183], v[240:243], v[76:79]
	v_mfma_f32_16x16x32_bf16 v[72:75], v[188:191], v[240:243], v[72:75]
	v_mfma_f32_16x16x32_bf16 v[116:119], v[192:195], v[212:215], v[116:119]
	v_mfma_f32_16x16x32_bf16 v[112:115], v[204:207], v[212:215], v[112:115]
	v_mfma_f32_16x16x32_bf16 v[100:103], v[192:195], v[220:223], v[100:103]
	v_mfma_f32_16x16x32_bf16 v[96:99], v[204:207], v[220:223], v[96:99]
	v_mfma_f32_16x16x32_bf16 v[84:87], v[192:195], v[228:231], v[84:87]
	v_mfma_f32_16x16x32_bf16 v[80:83], v[204:207], v[228:231], v[80:83]
	v_mfma_f32_16x16x32_bf16 v[68:71], v[192:195], v[236:239], v[68:71]
	v_mfma_f32_16x16x32_bf16 v[64:67], v[204:207], v[236:239], v[64:67]
	v_mfma_f32_16x16x32_bf16 v[116:119], v[196:199], v[216:219], v[116:119]
	v_mfma_f32_16x16x32_bf16 v[112:115], v[208:211], v[216:219], v[112:115]
	v_mfma_f32_16x16x32_bf16 v[100:103], v[196:199], v[224:227], v[100:103]
	v_mfma_f32_16x16x32_bf16 v[96:99], v[208:211], v[224:227], v[96:99]
	v_mfma_f32_16x16x32_bf16 v[84:87], v[196:199], v[232:235], v[84:87]
	v_mfma_f32_16x16x32_bf16 v[80:83], v[208:211], v[232:235], v[80:83]
	v_mfma_f32_16x16x32_bf16 v[68:71], v[196:199], v[240:243], v[68:71]
	v_mfma_f32_16x16x32_bf16 v[64:67], v[208:211], v[240:243], v[64:67]
	s_barrier
; #define PG8_STAGE(bufoff, gbase, voff) do { _Pragma("unroll") for (int _i = 0; _i < 2; ++_i) \
;         __builtin_amdgcn_global_load_lds((const unsigned*)((const char*)(gbase) + (voff)[_i]), (LAS unsigned*)(lds + (bufoff) + ldsw + _i * 8192), 16, 0, 0); } while (0)
; #define PG8_LDA(dst, b, h) do { _Pragma("unroll") for (int m = 0; m < 4; ++m) _Pragma("unroll") for (int k = 0; k < 2; ++k) dst[m][k] = *(const LAS bf16x8*)(lds + PG8_SA(b, h) + aoff + m * 2048 + k * 1024); } while (0)
; #define PG8_MMA(ai, bj, At, Bt) do { __builtin_amdgcn_s_setprio(1); _Pragma("unroll") for (int m = 0; m < 4; ++m) _Pragma("unroll") for (int n = 0; n < 2; ++n) _Pragma("unroll") for (int k = 0; k < 2; ++k) \
;         acc[ai][bj][m][n] = __builtin_amdgcn_mfma_f32_16x16x32_bf16(Bt[n][k], At[m][k], acc[ai][bj][m][n], 0, 0, 0); __builtin_amdgcn_s_setprio(0); } while (0)
; #define PG8_WAIT_V(n) asm volatile("s_waitcnt vmcnt(" #n ")" ::: "memory")
; #define PG8_WAIT_L(n) asm volatile("s_waitcnt lgkmcnt(" #n ")" ::: "memory")
; #define PG8_BAR __builtin_amdgcn_s_barrier()
; #define PG8_SCHED __builtin_amdgcn_sched_barrier(0)
; template <class Epi, class Sched, bool ALIGN_EPI = true>
; __device__ __forceinline__ void gemm_phase(LAS unsigned char* lds, const Gemm g, const Sched& S, const Epi& E) {
;     ...
;             PG8_LDA(At, 1, 1); PG8_STAGE(PG8_SB(1, 0), b3, voffB); PG8_STAGE(PG8_SB(1, 1), b3 + hstep, voffB); PG8_STAGE(PG8_SA(1, 0), a3, voffA);
;             PG8_WAIT_V(8); PG8_WAIT_L(0); PG8_BAR; PG8_MMA(1, 0, At, B0); PG8_MMA(1, 1, At, B1); PG8_BAR; PG8_SCHED;
;         }
	s_add_i32 s38, s46, s42
	v_lshl_add_u64 v[164:165], v[164:165], 0, s[22:23]
	s_mov_b32 m0, s38
	ds_read_b128 v[212:215], v171 offset:49152
	ds_read_b128 v[216:219], v171 offset:50176
	ds_read_b128 v[220:223], v171 offset:51200
	ds_read_b128 v[224:227], v171 offset:52224
	ds_read_b128 v[228:231], v171 offset:53248
	ds_read_b128 v[232:235], v171 offset:54272
	ds_read_b128 v[236:239], v171 offset:55296
	ds_read_b128 v[240:243], v171 offset:56320
	global_load_lds_dwordx4 v[164:165], off
	s_add_i32 m0, s38, 0x2000
	s_add_u32 s36, s36, 0x80080
	v_lshl_add_u64 v[164:165], v[176:177], 0, s[22:23]
	s_addc_u32 s37, s37, 0
	s_add_i32 s38, s47, s42
	global_load_lds_dwordx4 v[164:165], off
	s_mov_b32 m0, s38
	v_lshl_add_u64 v[164:165], s[36:37], 0, v[130:131]
	global_load_lds_dwordx4 v[164:165], off
	s_add_i32 m0, s38, 0x2000
	v_lshl_add_u64 v[164:165], s[36:37], 0, v[134:135]
	global_load_lds_dwordx4 v[164:165], off
	s_mov_b32 m0, s54
	v_lshl_add_u64 v[164:165], v[200:201], 0, s[22:23]
	global_load_lds_dwordx4 v[164:165], off
	s_mov_b32 m0, s55
	v_lshl_add_u64 v[164:165], v[244:245], 0, s[22:23]
	global_load_lds_dwordx4 v[164:165], off
	s_waitcnt vmcnt(8)
	s_waitcnt lgkmcnt(0)
	s_barrier
	s_waitcnt lgkmcnt(0)
	v_mfma_f32_16x16x32_bf16 v[60:63], v[172:175], v[212:215], v[60:63]
	v_mfma_f32_16x16x32_bf16 v[56:59], v[184:187], v[212:215], v[56:59]
	v_mfma_f32_16x16x32_bf16 v[44:47], v[172:175], v[220:223], v[44:47]
	v_mfma_f32_16x16x32_bf16 v[40:43], v[184:187], v[220:223], v[40:43]
	v_mfma_f32_16x16x32_bf16 v[28:31], v[172:175], v[228:231], v[28:31]
	v_mfma_f32_16x16x32_bf16 v[24:27], v[184:187], v[228:231], v[24:27]
	v_mfma_f32_16x16x32_bf16 v[12:15], v[172:175], v[236:239], v[12:15]
	v_mfma_f32_16x16x32_bf16 v[8:11], v[184:187], v[236:239], v[8:11]
	v_mfma_f32_16x16x32_bf16 v[60:63], v[180:183], v[216:219], v[60:63]
	v_mfma_f32_16x16x32_bf16 v[56:59], v[188:191], v[216:219], v[56:59]
	v_mfma_f32_16x16x32_bf16 v[44:47], v[180:183], v[224:227], v[44:47]
	v_mfma_f32_16x16x32_bf16 v[40:43], v[188:191], v[224:227], v[40:43]
	v_mfma_f32_16x16x32_bf16 v[28:31], v[180:183], v[232:235], v[28:31]
	v_mfma_f32_16x16x32_bf16 v[24:27], v[188:191], v[232:235], v[24:27]
	v_mfma_f32_16x16x32_bf16 v[12:15], v[180:183], v[240:243], v[12:15]
	v_mfma_f32_16x16x32_bf16 v[8:11], v[188:191], v[240:243], v[8:11]
	v_mfma_f32_16x16x32_bf16 v[52:55], v[192:195], v[212:215], v[52:55]
	v_mfma_f32_16x16x32_bf16 v[48:51], v[204:207], v[212:215], v[48:51]
	v_mfma_f32_16x16x32_bf16 v[36:39], v[192:195], v[220:223], v[36:39]
	v_mfma_f32_16x16x32_bf16 v[32:35], v[204:207], v[220:223], v[32:35]
	v_mfma_f32_16x16x32_bf16 v[20:23], v[192:195], v[228:231], v[20:23]
	v_mfma_f32_16x16x32_bf16 v[16:19], v[204:207], v[228:231], v[16:19]
	v_mfma_f32_16x16x32_bf16 v[4:7], v[192:195], v[236:239], v[4:7]
	v_mfma_f32_16x16x32_bf16 v[0:3], v[204:207], v[236:239], v[0:3]
	v_mfma_f32_16x16x32_bf16 v[52:55], v[196:199], v[216:219], v[52:55]
	v_mfma_f32_16x16x32_bf16 v[48:51], v[208:211], v[216:219], v[48:51]
	v_mfma_f32_16x16x32_bf16 v[36:39], v[196:199], v[224:227], v[36:39]
	v_mfma_f32_16x16x32_bf16 v[32:35], v[208:211], v[224:227], v[32:35]
	v_mfma_f32_16x16x32_bf16 v[20:23], v[196:199], v[232:235], v[20:23]
	v_mfma_f32_16x16x32_bf16 v[16:19], v[208:211], v[232:235], v[16:19]
	v_mfma_f32_16x16x32_bf16 v[4:7], v[196:199], v[240:243], v[4:7]
	v_mfma_f32_16x16x32_bf16 v[0:3], v[208:211], v[240:243], v[0:3]
	s_add_i32 s89, s89, 2
	s_add_u32 s34, s34, 0x100
	s_addc_u32 s35, s35, 0
	s_add_u32 s87, s87, 0x100
	s_addc_u32 s88, s88, 0
	s_cmp_gt_u32 s89, 29
	s_barrier
	s_cbranch_scc0 .LBB0_195
	s_and_b64 vcc, exec, s[24:25]
	s_cbranch_vccnz .LBB0_202
	s_lshr_b32 s9, s81, 2
	s_cmp_lt_i32 s9, 1
	s_mov_b64 s[34:35], -1
	s_cbranch_scc0 .LBB0_203

; #define PG8_STAGE(bufoff, gbase, voff) do { _Pragma("unroll") for (int _i = 0; _i < 2; ++_i) \
;         __builtin_amdgcn_global_load_lds((const unsigned*)((const char*)(gbase) + (voff)[_i]), (LAS unsigned*)(lds + (bufoff) + ldsw + _i * 8192), 16, 0, 0); } while (0)
; #define PG8_LDA(dst, b, h) do { _Pragma("unroll") for (int m = 0; m < 4; ++m) _Pragma("unroll") for (int k = 0; k < 2; ++k) dst[m][k] = *(const LAS bf16x8*)(lds + PG8_SA(b, h) + aoff + m * 2048 + k * 1024); } while (0)
; #define PG8_LDB(dst, b, h) do { _Pragma("unroll") for (int n = 0; n < 2; ++n) _Pragma("unroll") for (int k = 0; k < 2; ++k) dst[n][k] = *(const LAS bf16x8*)(lds + PG8_SB(b, h) + boff + n * 2048 + k * 1024); } while (0)
; #define PG8_MMA(ai, bj, At, Bt) do { __builtin_amdgcn_s_setprio(1); _Pragma("unroll") for (int m = 0; m < 4; ++m) _Pragma("unroll") for (int n = 0; n < 2; ++n) _Pragma("unroll") for (int k = 0; k < 2; ++k) \
;         acc[ai][bj][m][n] = __builtin_amdgcn_mfma_f32_16x16x32_bf16(Bt[n][k], At[m][k], acc[ai][bj][m][n], 0, 0, 0); __builtin_amdgcn_s_setprio(0); } while (0)
; #define PG8_WAIT_V(n) asm volatile("s_waitcnt vmcnt(" #n ")" ::: "memory")
; #define PG8_WAIT_L(n) asm volatile("s_waitcnt lgkmcnt(" #n ")" ::: "memory")
; #define PG8_BAR __builtin_amdgcn_s_barrier()
; #define PG8_SCHED __builtin_amdgcn_sched_barrier(0)
; template <class Epi, class Sched, bool ALIGN_EPI = true>
; __device__ __forceinline__ void gemm_phase(LAS unsigned char* lds, const Gemm g, const Sched& S, const Epi& E) {
;     ...
;             PG8_LDB(B0, 0, 0); PG8_LDB(B1, 0, 1); PG8_SCHED; PG8_LDA(At, 0, 0); PG8_STAGE(PG8_SA(1, 1), a1 + hstep, voffA);
;             PG8_WAIT_V(8); PG8_WAIT_L(0); PG8_BAR; PG8_MMA(0, 0, At, B0); PG8_MMA(0, 1, At, B1); PG8_BAR; PG8_SCHED;
;             PG8_LDA(At, 0, 1); PG8_STAGE(PG8_SB(0, 0), b2, voffB); PG8_STAGE(PG8_SB(0, 1), b2 + hstep, voffB); PG8_STAGE(PG8_SA(0, 0), a2, voffA);
;             PG8_WAIT_V(8); PG8_WAIT_L(0); PG8_BAR; PG8_MMA(1, 0, At, B0); PG8_MMA(1, 1, At, B1); PG8_BAR; PG8_SCHED;
.LBB0_223:
	ds_read_b128 v[128:131], v203
	s_waitcnt lgkmcnt(0)
	ds_read_b128 v[132:135], v203 offset:1024
	ds_read_b128 v[136:139], v203 offset:2048
	ds_read_b128 v[140:143], v203 offset:3072
	ds_read_b128 v[176:179], v204
	ds_read_b128 v[180:183], v204 offset:1024
	ds_read_b128 v[184:187], v204 offset:2048
	ds_read_b128 v[188:191], v204 offset:3072
	s_add_u32 s46, s76, 0xfff80080
	s_addc_u32 s47, s77, -1
	s_cmp_eq_u32 vcc_hi, 28
	s_cselect_b32 s81, s9, s47
	s_cselect_b32 s80, s30, s46
	s_cselect_b32 s79, s11, vcc_lo
	s_cselect_b32 s78, s96, s97
	v_lshl_add_u64 v[200:201], s[76:77], 0, v[164:165]
	s_add_i32 m0, s55, 0xc000
	ds_read_b128 v[192:195], v205
	ds_read_b128 v[196:199], v205 offset:1024
	ds_read_b128 v[208:211], v205 offset:2048
	ds_read_b128 v[212:215], v205 offset:3072
	ds_read_b128 v[216:219], v205 offset:4096
	ds_read_b128 v[220:223], v205 offset:5120
	ds_read_b128 v[224:227], v205 offset:6144
	ds_read_b128 v[228:231], v205 offset:7168
	global_load_lds_dwordx4 v[200:201], off
	s_add_i32 m0, s55, 0xe000
	v_lshl_add_u64 v[200:201], s[76:77], 0, v[166:167]
	global_load_lds_dwordx4 v[200:201], off
	s_waitcnt vmcnt(8)
	s_waitcnt lgkmcnt(0)
	s_barrier
	s_waitcnt lgkmcnt(0)
	v_mfma_f32_16x16x32_bf16 v[124:127], v[128:131], v[192:195], v[124:127]
	v_mfma_f32_16x16x32_bf16 v[120:123], v[136:139], v[192:195], v[120:123]
	v_mfma_f32_16x16x32_bf16 v[108:111], v[128:131], v[208:211], v[108:111]
	v_mfma_f32_16x16x32_bf16 v[104:107], v[136:139], v[208:211], v[104:107]
	v_mfma_f32_16x16x32_bf16 v[92:95], v[128:131], v[216:219], v[92:95]
	v_mfma_f32_16x16x32_bf16 v[88:91], v[136:139], v[216:219], v[88:91]
	v_mfma_f32_16x16x32_bf16 v[76:79], v[128:131], v[224:227], v[76:79]
	v_mfma_f32_16x16x32_bf16 v[72:75], v[136:139], v[224:227], v[72:75]
	v_mfma_f32_16x16x32_bf16 v[124:127], v[132:135], v[196:199], v[124:127]
	v_mfma_f32_16x16x32_bf16 v[120:123], v[140:143], v[196:199], v[120:123]
	v_mfma_f32_16x16x32_bf16 v[108:111], v[132:135], v[212:215], v[108:111]
	v_mfma_f32_16x16x32_bf16 v[104:107], v[140:143], v[212:215], v[104:107]
	v_mfma_f32_16x16x32_bf16 v[92:95], v[132:135], v[220:223], v[92:95]
	v_mfma_f32_16x16x32_bf16 v[88:91], v[140:143], v[220:223], v[88:91]
	v_mfma_f32_16x16x32_bf16 v[76:79], v[132:135], v[228:231], v[76:79]
	v_mfma_f32_16x16x32_bf16 v[72:75], v[140:143], v[228:231], v[72:75]
	v_mfma_f32_16x16x32_bf16 v[116:119], v[176:179], v[192:195], v[116:119]
	v_mfma_f32_16x16x32_bf16 v[112:115], v[184:187], v[192:195], v[112:115]
	v_mfma_f32_16x16x32_bf16 v[100:103], v[176:179], v[208:211], v[100:103]
	v_mfma_f32_16x16x32_bf16 v[96:99], v[184:187], v[208:211], v[96:99]
	v_mfma_f32_16x16x32_bf16 v[84:87], v[176:179], v[216:219], v[84:87]
	v_mfma_f32_16x16x32_bf16 v[80:83], v[184:187], v[216:219], v[80:83]
	v_mfma_f32_16x16x32_bf16 v[68:71], v[176:179], v[224:227], v[68:71]
	v_mfma_f32_16x16x32_bf16 v[64:67], v[184:187], v[224:227], v[64:67]
	v_mfma_f32_16x16x32_bf16 v[116:119], v[180:183], v[196:199], v[116:119]
	v_mfma_f32_16x16x32_bf16 v[112:115], v[188:191], v[196:199], v[112:115]
	v_mfma_f32_16x16x32_bf16 v[100:103], v[180:183], v[212:215], v[100:103]
	v_mfma_f32_16x16x32_bf16 v[96:99], v[188:191], v[212:215], v[96:99]
	v_mfma_f32_16x16x32_bf16 v[84:87], v[180:183], v[220:223], v[84:87]
	v_mfma_f32_16x16x32_bf16 v[80:83], v[188:191], v[220:223], v[80:83]
	v_mfma_f32_16x16x32_bf16 v[68:71], v[180:183], v[228:231], v[68:71]
	v_mfma_f32_16x16x32_bf16 v[64:67], v[188:191], v[228:231], v[64:67]
	s_barrier
	s_add_i32 s46, s90, s53
	v_lshl_add_u64 v[200:201], s[78:79], 0, v[146:147]
	s_mov_b32 m0, s46
	ds_read_b128 v[192:195], v205 offset:16384
	ds_read_b128 v[196:199], v205 offset:17408
	ds_read_b128 v[208:211], v205 offset:18432
	ds_read_b128 v[212:215], v205 offset:19456
	ds_read_b128 v[216:219], v205 offset:20480
	ds_read_b128 v[220:223], v205 offset:21504
	ds_read_b128 v[224:227], v205 offset:22528
	ds_read_b128 v[228:231], v205 offset:23552
	global_load_lds_dwordx4 v[200:201], off
	s_add_i32 m0, s46, 0x2000
	s_add_u32 s46, s78, 0x80000
	v_lshl_add_u64 v[232:233], s[78:79], 0, v[150:151]
	s_addc_u32 s47, s79, 0
	s_add_i32 s82, s91, s53
	global_load_lds_dwordx4 v[232:233], off
	v_lshl_add_u64 v[234:235], s[46:47], 0, v[146:147]
	s_mov_b32 m0, s82
	v_lshl_add_u64 v[236:237], s[80:81], 0, v[148:149]
	global_load_lds_dwordx4 v[234:235], off
	s_add_i32 m0, s82, 0x2000
	v_lshl_add_u64 v[234:235], s[46:47], 0, v[150:151]
	global_load_lds_dwordx4 v[234:235], off
	s_mov_b32 m0, s55
	v_lshl_add_u64 v[234:235], s[80:81], 0, v[144:145]
	global_load_lds_dwordx4 v[234:235], off
	s_mov_b32 m0, s57
	s_nop 0
	global_load_lds_dwordx4 v[236:237], off
	s_waitcnt vmcnt(8)
	s_waitcnt lgkmcnt(0)
	s_barrier
; #define PG8_STAGE(bufoff, gbase, voff) do { _Pragma("unroll") for (int _i = 0; _i < 2; ++_i) \
;         __builtin_amdgcn_global_load_lds((const unsigned*)((const char*)(gbase) + (voff)[_i]), (LAS unsigned*)(lds + (bufoff) + ldsw + _i * 8192), 16, 0, 0); } while (0)
; #define PG8_LDA(dst, b, h) do { _Pragma("unroll") for (int m = 0; m < 4; ++m) _Pragma("unroll") for (int k = 0; k < 2; ++k) dst[m][k] = *(const LAS bf16x8*)(lds + PG8_SA(b, h) + aoff + m * 2048 + k * 1024); } while (0)
; #define PG8_LDB(dst, b, h) do { _Pragma("unroll") for (int n = 0; n < 2; ++n) _Pragma("unroll") for (int k = 0; k < 2; ++k) dst[n][k] = *(const LAS bf16x8*)(lds + PG8_SB(b, h) + boff + n * 2048 + k * 1024); } while (0)
; #define PG8_MMA(ai, bj, At, Bt) do { __builtin_amdgcn_s_setprio(1); _Pragma("unroll") for (int m = 0; m < 4; ++m) _Pragma("unroll") for (int n = 0; n < 2; ++n) _Pragma("unroll") for (int k = 0; k < 2; ++k) \
;         acc[ai][bj][m][n] = __builtin_amdgcn_mfma_f32_16x16x32_bf16(Bt[n][k], At[m][k], acc[ai][bj][m][n], 0, 0, 0); __builtin_amdgcn_s_setprio(0); } while (0)
; #define PG8_WAIT_V(n) asm volatile("s_waitcnt vmcnt(" #n ")" ::: "memory")
; #define PG8_WAIT_L(n) asm volatile("s_waitcnt lgkmcnt(" #n ")" ::: "memory")
; #define PG8_BAR __builtin_amdgcn_s_barrier()
; #define PG8_SCHED __builtin_amdgcn_sched_barrier(0)
; template <class Epi, class Sched, bool ALIGN_EPI = true>
; __device__ __forceinline__ void gemm_phase(LAS unsigned char* lds, const Gemm g, const Sched& S, const Epi& E) {
;     ...
;             PG8_WAIT_V(8); PG8_WAIT_L(0); PG8_BAR; PG8_MMA(1, 0, At, B0); PG8_MMA(1, 1, At, B1); PG8_BAR; PG8_SCHED;
;             PG8_LDB(B0, 1, 0); PG8_LDB(B1, 1, 1); PG8_SCHED; PG8_LDA(At, 1, 0); PG8_STAGE(PG8_SA(0, 1), a2 + hstep, voffA);
;             PG8_WAIT_V(8); PG8_WAIT_L(0); PG8_BAR; PG8_MMA(0, 0, At, B0); PG8_MMA(0, 1, At, B1); PG8_BAR; PG8_SCHED;
	s_waitcnt lgkmcnt(0)
	v_mfma_f32_16x16x32_bf16 v[60:63], v[128:131], v[192:195], v[60:63]
	v_mfma_f32_16x16x32_bf16 v[56:59], v[136:139], v[192:195], v[56:59]
	v_mfma_f32_16x16x32_bf16 v[44:47], v[128:131], v[208:211], v[44:47]
	v_mfma_f32_16x16x32_bf16 v[40:43], v[136:139], v[208:211], v[40:43]
	v_mfma_f32_16x16x32_bf16 v[28:31], v[128:131], v[216:219], v[28:31]
	v_mfma_f32_16x16x32_bf16 v[24:27], v[136:139], v[216:219], v[24:27]
	v_mfma_f32_16x16x32_bf16 v[12:15], v[128:131], v[224:227], v[12:15]
	v_mfma_f32_16x16x32_bf16 v[8:11], v[136:139], v[224:227], v[8:11]
	v_mfma_f32_16x16x32_bf16 v[60:63], v[132:135], v[196:199], v[60:63]
	v_mfma_f32_16x16x32_bf16 v[56:59], v[140:143], v[196:199], v[56:59]
	v_mfma_f32_16x16x32_bf16 v[44:47], v[132:135], v[212:215], v[44:47]
	v_mfma_f32_16x16x32_bf16 v[40:43], v[140:143], v[212:215], v[40:43]
	v_mfma_f32_16x16x32_bf16 v[28:31], v[132:135], v[220:223], v[28:31]
	v_mfma_f32_16x16x32_bf16 v[24:27], v[140:143], v[220:223], v[24:27]
	v_mfma_f32_16x16x32_bf16 v[12:15], v[132:135], v[228:231], v[12:15]
	v_mfma_f32_16x16x32_bf16 v[8:11], v[140:143], v[228:231], v[8:11]
	v_mfma_f32_16x16x32_bf16 v[52:55], v[176:179], v[192:195], v[52:55]
	v_mfma_f32_16x16x32_bf16 v[48:51], v[184:187], v[192:195], v[48:51]
	v_mfma_f32_16x16x32_bf16 v[36:39], v[176:179], v[208:211], v[36:39]
	v_mfma_f32_16x16x32_bf16 v[32:35], v[184:187], v[208:211], v[32:35]
	v_mfma_f32_16x16x32_bf16 v[20:23], v[176:179], v[216:219], v[20:23]
	v_mfma_f32_16x16x32_bf16 v[16:19], v[184:187], v[216:219], v[16:19]
	v_mfma_f32_16x16x32_bf16 v[4:7], v[176:179], v[224:227], v[4:7]
	v_mfma_f32_16x16x32_bf16 v[0:3], v[184:187], v[224:227], v[0:3]
	v_mfma_f32_16x16x32_bf16 v[52:55], v[180:183], v[196:199], v[52:55]
	v_mfma_f32_16x16x32_bf16 v[48:51], v[188:191], v[196:199], v[48:51]
	v_mfma_f32_16x16x32_bf16 v[36:39], v[180:183], v[212:215], v[36:39]
	v_mfma_f32_16x16x32_bf16 v[32:35], v[188:191], v[212:215], v[32:35]
	v_mfma_f32_16x16x32_bf16 v[20:23], v[180:183], v[220:223], v[20:23]
	v_mfma_f32_16x16x32_bf16 v[16:19], v[188:191], v[220:223], v[16:19]
	v_mfma_f32_16x16x32_bf16 v[4:7], v[180:183], v[228:231], v[4:7]
	v_mfma_f32_16x16x32_bf16 v[0:3], v[188:191], v[228:231], v[0:3]
	s_barrier
	s_add_i32 s82, 0, 0x18000
	s_add_i32 s92, 0, 0x1c000
	v_add_u32_e32 v140, s82, v161
	v_add_u32_e32 v152, s92, v161
	ds_read_b128 v[128:131], v140
	ds_read_b128 v[132:135], v140 offset:1024
	ds_read_b128 v[136:139], v140 offset:2048
	ds_read_b128 v[140:143], v140 offset:3072
	ds_read_b128 v[176:179], v152
	ds_read_b128 v[180:183], v152 offset:1024
	ds_read_b128 v[184:187], v152 offset:2048
	ds_read_b128 v[188:191], v152 offset:3072
	s_add_u32 s46, s80, 0x80000
	s_addc_u32 s47, s81, 0
	s_mov_b32 m0, s83
	v_lshl_add_u64 v[238:239], s[46:47], 0, v[144:145]
	ds_read_b128 v[192:195], v205 offset:32768
	ds_read_b128 v[196:199], v205 offset:33792
	ds_read_b128 v[208:211], v205 offset:34816
	ds_read_b128 v[212:215], v205 offset:35840
	ds_read_b128 v[216:219], v205 offset:36864
	ds_read_b128 v[220:223], v205 offset:37888
	ds_read_b128 v[224:227], v205 offset:38912
	ds_read_b128 v[228:231], v205 offset:39936
	global_load_lds_dwordx4 v[238:239], off
	s_mov_b32 m0, s84
	v_lshl_add_u64 v[238:239], s[46:47], 0, v[148:149]
	global_load_lds_dwordx4 v[238:239], off
	s_waitcnt vmcnt(8)
	s_waitcnt lgkmcnt(0)
	s_barrier
	s_waitcnt lgkmcnt(0)
	v_mfma_f32_16x16x32_bf16 v[124:127], v[128:131], v[192:195], v[124:127]
	v_mfma_f32_16x16x32_bf16 v[120:123], v[136:139], v[192:195], v[120:123]
	v_mfma_f32_16x16x32_bf16 v[108:111], v[128:131], v[208:211], v[108:111]
	v_mfma_f32_16x16x32_bf16 v[104:107], v[136:139], v[208:211], v[104:107]
	v_mfma_f32_16x16x32_bf16 v[92:95], v[128:131], v[216:219], v[92:95]
	v_mfma_f32_16x16x32_bf16 v[88:91], v[136:139], v[216:219], v[88:91]
	v_mfma_f32_16x16x32_bf16 v[76:79], v[128:131], v[224:227], v[76:79]
	v_mfma_f32_16x16x32_bf16 v[72:75], v[136:139], v[224:227], v[72:75]
	v_mfma_f32_16x16x32_bf16 v[124:127], v[132:135], v[196:199], v[124:127]
	v_mfma_f32_16x16x32_bf16 v[120:123], v[140:143], v[196:199], v[120:123]
	v_mfma_f32_16x16x32_bf16 v[108:111], v[132:135], v[212:215], v[108:111]
	v_mfma_f32_16x16x32_bf16 v[104:107], v[140:143], v[212:215], v[104:107]
	v_mfma_f32_16x16x32_bf16 v[92:95], v[132:135], v[220:223], v[92:95]
	v_mfma_f32_16x16x32_bf16 v[88:91], v[140:143], v[220:223], v[88:91]
	v_mfma_f32_16x16x32_bf16 v[76:79], v[132:135], v[228:231], v[76:79]
	v_mfma_f32_16x16x32_bf16 v[72:75], v[140:143], v[228:231], v[72:75]
	v_mfma_f32_16x16x32_bf16 v[116:119], v[176:179], v[192:195], v[116:119]
	v_mfma_f32_16x16x32_bf16 v[112:115], v[184:187], v[192:195], v[112:115]
	v_mfma_f32_16x16x32_bf16 v[100:103], v[176:179], v[208:211], v[100:103]
	v_mfma_f32_16x16x32_bf16 v[96:99], v[184:187], v[208:211], v[96:99]
	v_mfma_f32_16x16x32_bf16 v[84:87], v[176:179], v[216:219], v[84:87]
	v_mfma_f32_16x16x32_bf16 v[80:83], v[184:187], v[216:219], v[80:83]
	v_mfma_f32_16x16x32_bf16 v[68:71], v[176:179], v[224:227], v[68:71]
	v_mfma_f32_16x16x32_bf16 v[64:67], v[184:187], v[224:227], v[64:67]
	v_mfma_f32_16x16x32_bf16 v[116:119], v[180:183], v[196:199], v[116:119]
	v_mfma_f32_16x16x32_bf16 v[112:115], v[188:191], v[196:199], v[112:115]
	v_mfma_f32_16x16x32_bf16 v[100:103], v[180:183], v[212:215], v[100:103]
	v_mfma_f32_16x16x32_bf16 v[96:99], v[188:191], v[212:215], v[96:99]
	v_mfma_f32_16x16x32_bf16 v[84:87], v[180:183], v[220:223], v[84:87]
	v_mfma_f32_16x16x32_bf16 v[80:83], v[188:191], v[220:223], v[80:83]
	v_mfma_f32_16x16x32_bf16 v[68:71], v[180:183], v[228:231], v[68:71]
	v_mfma_f32_16x16x32_bf16 v[64:67], v[188:191], v[228:231], v[64:67]
	s_barrier
; #define PG8_STAGE(bufoff, gbase, voff) do { _Pragma("unroll") for (int _i = 0; _i < 2; ++_i) \
;         __builtin_amdgcn_global_load_lds((const unsigned*)((const char*)(gbase) + (voff)[_i]), (LAS unsigned*)(lds + (bufoff) + ldsw + _i * 8192), 16, 0, 0); } while (0)
; #define PG8_LDA(dst, b, h) do { _Pragma("unroll") for (int m = 0; m < 4; ++m) _Pragma("unroll") for (int k = 0; k < 2; ++k) dst[m][k] = *(const LAS bf16x8*)(lds + PG8_SA(b, h) + aoff + m * 2048 + k * 1024); } while (0)
; #define PG8_MMA(ai, bj, At, Bt) do { __builtin_amdgcn_s_setprio(1); _Pragma("unroll") for (int m = 0; m < 4; ++m) _Pragma("unroll") for (int n = 0; n < 2; ++n) _Pragma("unroll") for (int k = 0; k < 2; ++k) \
;         acc[ai][bj][m][n] = __builtin_amdgcn_mfma_f32_16x16x32_bf16(Bt[n][k], At[m][k], acc[ai][bj][m][n], 0, 0, 0); __builtin_amdgcn_s_setprio(0); } while (0)
; #define PG8_WAIT_V(n) asm volatile("s_waitcnt vmcnt(" #n ")" ::: "memory")
; #define PG8_WAIT_L(n) asm volatile("s_waitcnt lgkmcnt(" #n ")" ::: "memory")
; #define PG8_BAR __builtin_amdgcn_s_barrier()
; #define PG8_SCHED __builtin_amdgcn_sched_barrier(0)
; template <class Epi, class Sched, bool ALIGN_EPI = true>
; __device__ __forceinline__ void gemm_phase(LAS unsigned char* lds, const Gemm g, const Sched& S, const Epi& E) {
;     ...
;             PG8_LDA(At, 1, 1); PG8_STAGE(PG8_SB(1, 0), b3, voffB); PG8_STAGE(PG8_SB(1, 1), b3 + hstep, voffB); PG8_STAGE(PG8_SA(1, 0), a3, voffA);
;             PG8_WAIT_V(8); PG8_WAIT_L(0); PG8_BAR; PG8_MMA(1, 0, At, B0); PG8_MMA(1, 1, At, B1); PG8_BAR; PG8_SCHED;
;         }
	s_add_i32 s46, s82, s53
	v_lshl_add_u64 v[200:201], v[200:201], 0, s[28:29]
	s_mov_b32 m0, s46
	ds_read_b128 v[192:195], v205 offset:49152
	ds_read_b128 v[196:199], v205 offset:50176
	ds_read_b128 v[208:211], v205 offset:51200
	ds_read_b128 v[212:215], v205 offset:52224
	ds_read_b128 v[216:219], v205 offset:53248
	ds_read_b128 v[220:223], v205 offset:54272
	ds_read_b128 v[224:227], v205 offset:55296
	ds_read_b128 v[228:231], v205 offset:56320
	global_load_lds_dwordx4 v[200:201], off
	s_add_i32 m0, s46, 0x2000
	s_add_u32 s46, s78, 0x80080
	v_lshl_add_u64 v[200:201], v[232:233], 0, s[28:29]
	s_addc_u32 s47, s79, 0
	s_add_i32 s78, s92, s53
	global_load_lds_dwordx4 v[200:201], off
	s_mov_b32 m0, s78
	v_lshl_add_u64 v[200:201], s[46:47], 0, v[146:147]
	global_load_lds_dwordx4 v[200:201], off
	s_add_i32 m0, s78, 0x2000
	v_lshl_add_u64 v[200:201], s[46:47], 0, v[150:151]
	global_load_lds_dwordx4 v[200:201], off
	s_mov_b32 m0, s87
	v_lshl_add_u64 v[200:201], v[234:235], 0, s[28:29]
	global_load_lds_dwordx4 v[200:201], off
	s_mov_b32 m0, s88
	v_lshl_add_u64 v[200:201], v[236:237], 0, s[28:29]
	global_load_lds_dwordx4 v[200:201], off
	s_waitcnt vmcnt(8)
	s_waitcnt lgkmcnt(0)
	s_barrier
	s_waitcnt lgkmcnt(0)
	v_mfma_f32_16x16x32_bf16 v[60:63], v[128:131], v[192:195], v[60:63]
	v_mfma_f32_16x16x32_bf16 v[56:59], v[136:139], v[192:195], v[56:59]
	v_mfma_f32_16x16x32_bf16 v[44:47], v[128:131], v[208:211], v[44:47]
	v_mfma_f32_16x16x32_bf16 v[40:43], v[136:139], v[208:211], v[40:43]
	v_mfma_f32_16x16x32_bf16 v[28:31], v[128:131], v[216:219], v[28:31]
	v_mfma_f32_16x16x32_bf16 v[24:27], v[136:139], v[216:219], v[24:27]
	v_mfma_f32_16x16x32_bf16 v[12:15], v[128:131], v[224:227], v[12:15]
	v_mfma_f32_16x16x32_bf16 v[8:11], v[136:139], v[224:227], v[8:11]
	v_mfma_f32_16x16x32_bf16 v[60:63], v[132:135], v[196:199], v[60:63]
	v_mfma_f32_16x16x32_bf16 v[56:59], v[140:143], v[196:199], v[56:59]
	v_mfma_f32_16x16x32_bf16 v[44:47], v[132:135], v[212:215], v[44:47]
	v_mfma_f32_16x16x32_bf16 v[40:43], v[140:143], v[212:215], v[40:43]
	v_mfma_f32_16x16x32_bf16 v[28:31], v[132:135], v[220:223], v[28:31]
	v_mfma_f32_16x16x32_bf16 v[24:27], v[140:143], v[220:223], v[24:27]
	v_mfma_f32_16x16x32_bf16 v[12:15], v[132:135], v[228:231], v[12:15]
	v_mfma_f32_16x16x32_bf16 v[8:11], v[140:143], v[228:231], v[8:11]
	v_mfma_f32_16x16x32_bf16 v[52:55], v[176:179], v[192:195], v[52:55]
	v_mfma_f32_16x16x32_bf16 v[48:51], v[184:187], v[192:195], v[48:51]
	v_mfma_f32_16x16x32_bf16 v[36:39], v[176:179], v[208:211], v[36:39]
	v_mfma_f32_16x16x32_bf16 v[32:35], v[184:187], v[208:211], v[32:35]
	v_mfma_f32_16x16x32_bf16 v[20:23], v[176:179], v[216:219], v[20:23]
	v_mfma_f32_16x16x32_bf16 v[16:19], v[184:187], v[216:219], v[16:19]
	v_mfma_f32_16x16x32_bf16 v[4:7], v[176:179], v[224:227], v[4:7]
	v_mfma_f32_16x16x32_bf16 v[0:3], v[184:187], v[224:227], v[0:3]
	v_mfma_f32_16x16x32_bf16 v[52:55], v[180:183], v[196:199], v[52:55]
	v_mfma_f32_16x16x32_bf16 v[48:51], v[188:191], v[196:199], v[48:51]
	v_mfma_f32_16x16x32_bf16 v[36:39], v[180:183], v[212:215], v[36:39]
	v_mfma_f32_16x16x32_bf16 v[32:35], v[188:191], v[212:215], v[32:35]
	v_mfma_f32_16x16x32_bf16 v[20:23], v[180:183], v[220:223], v[20:23]
	v_mfma_f32_16x16x32_bf16 v[16:19], v[188:191], v[220:223], v[16:19]
	v_mfma_f32_16x16x32_bf16 v[4:7], v[180:183], v[228:231], v[4:7]
	v_mfma_f32_16x16x32_bf16 v[0:3], v[188:191], v[228:231], v[0:3]
	s_add_i32 vcc_hi, vcc_hi, 2
	s_add_u32 s76, s76, 0x100
	s_addc_u32 s77, s77, 0
	s_add_u32 s97, s97, 0x100
	s_addc_u32 vcc_lo, vcc_lo, 0
	s_cmp_gt_u32 vcc_hi, 29
	s_barrier
	s_cbranch_scc0 .LBB0_223
	s_and_b64 vcc, exec, s[34:35]
	s_cbranch_vccz .LBB0_226
	s_barrier

; #define PG8_STAGE(bufoff, gbase, voff) do { _Pragma("unroll") for (int _i = 0; _i < 2; ++_i) \
;         __builtin_amdgcn_global_load_lds((const unsigned*)((const char*)(gbase) + (voff)[_i]), (LAS unsigned*)(lds + (bufoff) + ldsw + _i * 8192), 16, 0, 0); } while (0)
; #define PG8_LDA(dst, b, h) do { _Pragma("unroll") for (int m = 0; m < 4; ++m) _Pragma("unroll") for (int k = 0; k < 2; ++k) dst[m][k] = *(const LAS bf16x8*)(lds + PG8_SA(b, h) + aoff + m * 2048 + k * 1024); } while (0)
; #define PG8_LDB(dst, b, h) do { _Pragma("unroll") for (int n = 0; n < 2; ++n) _Pragma("unroll") for (int k = 0; k < 2; ++k) dst[n][k] = *(const LAS bf16x8*)(lds + PG8_SB(b, h) + boff + n * 2048 + k * 1024); } while (0)
; #define PG8_MMA(ai, bj, At, Bt) do { __builtin_amdgcn_s_setprio(1); _Pragma("unroll") for (int m = 0; m < 4; ++m) _Pragma("unroll") for (int n = 0; n < 2; ++n) _Pragma("unroll") for (int k = 0; k < 2; ++k) \
;         acc[ai][bj][m][n] = __builtin_amdgcn_mfma_f32_16x16x32_bf16(Bt[n][k], At[m][k], acc[ai][bj][m][n], 0, 0, 0); __builtin_amdgcn_s_setprio(0); } while (0)
; #define PG8_WAIT_V(n) asm volatile("s_waitcnt vmcnt(" #n ")" ::: "memory")
; #define PG8_WAIT_L(n) asm volatile("s_waitcnt lgkmcnt(" #n ")" ::: "memory")
; #define PG8_BAR __builtin_amdgcn_s_barrier()
; #define PG8_SCHED __builtin_amdgcn_sched_barrier(0)
; template <class Epi, class Sched, bool ALIGN_EPI = true>
; __device__ __forceinline__ void gemm_phase(LAS unsigned char* lds, const Gemm g, const Sched& S, const Epi& E) {
;     ...
;             PG8_LDB(B0, 0, 0); PG8_LDB(B1, 0, 1); PG8_SCHED; PG8_LDA(At, 0, 0); PG8_STAGE(PG8_SA(1, 1), a1 + hstep, voffA);
;             PG8_WAIT_V(8); PG8_WAIT_L(0); PG8_BAR; PG8_MMA(0, 0, At, B0); PG8_MMA(0, 1, At, B1); PG8_BAR; PG8_SCHED;
;             PG8_LDA(At, 0, 1); PG8_STAGE(PG8_SB(0, 0), b2, voffB); PG8_STAGE(PG8_SB(0, 1), b2 + hstep, voffB); PG8_STAGE(PG8_SA(0, 0), a2, voffA);
;             PG8_WAIT_V(8); PG8_WAIT_L(0); PG8_BAR; PG8_MMA(1, 0, At, B0); PG8_MMA(1, 1, At, B1); PG8_BAR; PG8_SCHED;
.LBB0_560:
	ds_read_b128 v[128:131], v206
	ds_read_b128 v[132:135], v206 offset:1024
	ds_read_b128 v[136:139], v206 offset:2048
	ds_read_b128 v[140:143], v206 offset:3072
	ds_read_b128 v[144:147], v207
	ds_read_b128 v[148:151], v207 offset:1024
	ds_read_b128 v[152:155], v207 offset:2048
	ds_read_b128 v[156:159], v207 offset:3072
	s_add_u32 s28, s26, 0xfff80080
	s_addc_u32 s29, s27, -1
	s_cmp_eq_u32 s58, 28
	s_cselect_b32 s31, s53, s29
	s_cselect_b32 s30, s54, s28
	s_cselect_b32 s29, s9, s57
	s_cselect_b32 s28, s55, s56
	v_lshl_add_u64 v[214:215], s[26:27], 0, v[184:185]
	s_add_i32 m0, s38, 0xc000
	ds_read_b128 v[160:163], v208
	ds_read_b128 v[164:167], v208 offset:1024
	ds_read_b128 v[168:171], v208 offset:2048
	ds_read_b128 v[172:175], v208 offset:3072
	ds_read_b128 v[188:191], v208 offset:4096
	ds_read_b128 v[192:195], v208 offset:5120
	ds_read_b128 v[196:199], v208 offset:6144
	ds_read_b128 v[210:213], v208 offset:7168
	global_load_lds_dwordx4 v[214:215], off
	s_add_i32 m0, s38, 0xe000
	v_lshl_add_u64 v[214:215], s[26:27], 0, v[186:187]
	global_load_lds_dwordx4 v[214:215], off
	s_waitcnt vmcnt(8)
	s_waitcnt lgkmcnt(0)
	s_barrier
	s_waitcnt lgkmcnt(0)
	v_mfma_f32_16x16x32_bf16 v[124:127], v[128:131], v[160:163], v[124:127]
	v_mfma_f32_16x16x32_bf16 v[120:123], v[136:139], v[160:163], v[120:123]
	v_mfma_f32_16x16x32_bf16 v[108:111], v[128:131], v[168:171], v[108:111]
	v_mfma_f32_16x16x32_bf16 v[104:107], v[136:139], v[168:171], v[104:107]
	v_mfma_f32_16x16x32_bf16 v[92:95], v[128:131], v[188:191], v[92:95]
	v_mfma_f32_16x16x32_bf16 v[88:91], v[136:139], v[188:191], v[88:91]
	v_mfma_f32_16x16x32_bf16 v[76:79], v[128:131], v[196:199], v[76:79]
	v_mfma_f32_16x16x32_bf16 v[72:75], v[136:139], v[196:199], v[72:75]
	v_mfma_f32_16x16x32_bf16 v[124:127], v[132:135], v[164:167], v[124:127]
	v_mfma_f32_16x16x32_bf16 v[120:123], v[140:143], v[164:167], v[120:123]
	v_mfma_f32_16x16x32_bf16 v[108:111], v[132:135], v[172:175], v[108:111]
	v_mfma_f32_16x16x32_bf16 v[104:107], v[140:143], v[172:175], v[104:107]
	v_mfma_f32_16x16x32_bf16 v[92:95], v[132:135], v[192:195], v[92:95]
	v_mfma_f32_16x16x32_bf16 v[88:91], v[140:143], v[192:195], v[88:91]
	v_mfma_f32_16x16x32_bf16 v[76:79], v[132:135], v[210:213], v[76:79]
	v_mfma_f32_16x16x32_bf16 v[72:75], v[140:143], v[210:213], v[72:75]
	v_mfma_f32_16x16x32_bf16 v[116:119], v[144:147], v[160:163], v[116:119]
	v_mfma_f32_16x16x32_bf16 v[112:115], v[152:155], v[160:163], v[112:115]
	v_mfma_f32_16x16x32_bf16 v[100:103], v[144:147], v[168:171], v[100:103]
	v_mfma_f32_16x16x32_bf16 v[96:99], v[152:155], v[168:171], v[96:99]
	v_mfma_f32_16x16x32_bf16 v[84:87], v[144:147], v[188:191], v[84:87]
	v_mfma_f32_16x16x32_bf16 v[80:83], v[152:155], v[188:191], v[80:83]
	v_mfma_f32_16x16x32_bf16 v[68:71], v[144:147], v[196:199], v[68:71]
	v_mfma_f32_16x16x32_bf16 v[64:67], v[152:155], v[196:199], v[64:67]
	v_mfma_f32_16x16x32_bf16 v[116:119], v[148:151], v[164:167], v[116:119]
	v_mfma_f32_16x16x32_bf16 v[112:115], v[156:159], v[164:167], v[112:115]
	v_mfma_f32_16x16x32_bf16 v[100:103], v[148:151], v[172:175], v[100:103]
	v_mfma_f32_16x16x32_bf16 v[96:99], v[156:159], v[172:175], v[96:99]
	v_mfma_f32_16x16x32_bf16 v[84:87], v[148:151], v[192:195], v[84:87]
	v_mfma_f32_16x16x32_bf16 v[80:83], v[156:159], v[192:195], v[80:83]
	v_mfma_f32_16x16x32_bf16 v[68:71], v[148:151], v[210:213], v[68:71]
	v_mfma_f32_16x16x32_bf16 v[64:67], v[156:159], v[210:213], v[64:67]
	s_barrier
	s_add_i32 s46, s44, s37
	v_lshl_add_u64 v[214:215], s[28:29], 0, v[178:179]
	s_mov_b32 m0, s46
	ds_read_b128 v[160:163], v208 offset:16384
	ds_read_b128 v[164:167], v208 offset:17408
	ds_read_b128 v[168:171], v208 offset:18432
	ds_read_b128 v[172:175], v208 offset:19456
	ds_read_b128 v[188:191], v208 offset:20480
	ds_read_b128 v[192:195], v208 offset:21504
	ds_read_b128 v[196:199], v208 offset:22528
	ds_read_b128 v[210:213], v208 offset:23552
	global_load_lds_dwordx4 v[214:215], off
	s_add_i32 m0, s46, 0x2000
	s_add_u32 s46, s28, 0x80000
	v_lshl_add_u64 v[216:217], s[28:29], 0, v[182:183]
	s_addc_u32 s47, s29, 0
	s_add_i32 s59, s45, s37
	global_load_lds_dwordx4 v[216:217], off
	v_lshl_add_u64 v[218:219], s[46:47], 0, v[178:179]
	s_mov_b32 m0, s59
	v_lshl_add_u64 v[220:221], s[30:31], 0, v[180:181]
	global_load_lds_dwordx4 v[218:219], off
	s_add_i32 m0, s59, 0x2000
	v_lshl_add_u64 v[218:219], s[46:47], 0, v[182:183]
	global_load_lds_dwordx4 v[218:219], off
	s_mov_b32 m0, s38
	v_lshl_add_u64 v[218:219], s[30:31], 0, v[176:177]
	global_load_lds_dwordx4 v[218:219], off
	s_mov_b32 m0, s39
	s_nop 0
	global_load_lds_dwordx4 v[220:221], off
	s_waitcnt vmcnt(8)
	s_waitcnt lgkmcnt(0)
	s_barrier
; #define PG8_STAGE(bufoff, gbase, voff) do { _Pragma("unroll") for (int _i = 0; _i < 2; ++_i) \
;         __builtin_amdgcn_global_load_lds((const unsigned*)((const char*)(gbase) + (voff)[_i]), (LAS unsigned*)(lds + (bufoff) + ldsw + _i * 8192), 16, 0, 0); } while (0)
; #define PG8_LDA(dst, b, h) do { _Pragma("unroll") for (int m = 0; m < 4; ++m) _Pragma("unroll") for (int k = 0; k < 2; ++k) dst[m][k] = *(const LAS bf16x8*)(lds + PG8_SA(b, h) + aoff + m * 2048 + k * 1024); } while (0)
; #define PG8_LDB(dst, b, h) do { _Pragma("unroll") for (int n = 0; n < 2; ++n) _Pragma("unroll") for (int k = 0; k < 2; ++k) dst[n][k] = *(const LAS bf16x8*)(lds + PG8_SB(b, h) + boff + n * 2048 + k * 1024); } while (0)
; #define PG8_MMA(ai, bj, At, Bt) do { __builtin_amdgcn_s_setprio(1); _Pragma("unroll") for (int m = 0; m < 4; ++m) _Pragma("unroll") for (int n = 0; n < 2; ++n) _Pragma("unroll") for (int k = 0; k < 2; ++k) \
;         acc[ai][bj][m][n] = __builtin_amdgcn_mfma_f32_16x16x32_bf16(Bt[n][k], At[m][k], acc[ai][bj][m][n], 0, 0, 0); __builtin_amdgcn_s_setprio(0); } while (0)
; #define PG8_WAIT_V(n) asm volatile("s_waitcnt vmcnt(" #n ")" ::: "memory")
; #define PG8_WAIT_L(n) asm volatile("s_waitcnt lgkmcnt(" #n ")" ::: "memory")
; #define PG8_BAR __builtin_amdgcn_s_barrier()
; #define PG8_SCHED __builtin_amdgcn_sched_barrier(0)
; template <class Epi, class Sched, bool ALIGN_EPI = true>
; __device__ __forceinline__ void gemm_phase(LAS unsigned char* lds, const Gemm g, const Sched& S, const Epi& E) {
;     ...
;             PG8_WAIT_V(8); PG8_WAIT_L(0); PG8_BAR; PG8_MMA(1, 0, At, B0); PG8_MMA(1, 1, At, B1); PG8_BAR; PG8_SCHED;
;             PG8_LDB(B0, 1, 0); PG8_LDB(B1, 1, 1); PG8_SCHED; PG8_LDA(At, 1, 0); PG8_STAGE(PG8_SA(0, 1), a2 + hstep, voffA);
;             PG8_WAIT_V(8); PG8_WAIT_L(0); PG8_BAR; PG8_MMA(0, 0, At, B0); PG8_MMA(0, 1, At, B1); PG8_BAR; PG8_SCHED;
	s_waitcnt lgkmcnt(0)
	v_mfma_f32_16x16x32_bf16 v[60:63], v[128:131], v[160:163], v[60:63]
	v_mfma_f32_16x16x32_bf16 v[56:59], v[136:139], v[160:163], v[56:59]
	v_mfma_f32_16x16x32_bf16 v[44:47], v[128:131], v[168:171], v[44:47]
	v_mfma_f32_16x16x32_bf16 v[40:43], v[136:139], v[168:171], v[40:43]
	v_mfma_f32_16x16x32_bf16 v[28:31], v[128:131], v[188:191], v[28:31]
	v_mfma_f32_16x16x32_bf16 v[24:27], v[136:139], v[188:191], v[24:27]
	v_mfma_f32_16x16x32_bf16 v[12:15], v[128:131], v[196:199], v[12:15]
	v_mfma_f32_16x16x32_bf16 v[8:11], v[136:139], v[196:199], v[8:11]
	v_mfma_f32_16x16x32_bf16 v[60:63], v[132:135], v[164:167], v[60:63]
	v_mfma_f32_16x16x32_bf16 v[56:59], v[140:143], v[164:167], v[56:59]
	v_mfma_f32_16x16x32_bf16 v[44:47], v[132:135], v[172:175], v[44:47]
	v_mfma_f32_16x16x32_bf16 v[40:43], v[140:143], v[172:175], v[40:43]
	v_mfma_f32_16x16x32_bf16 v[28:31], v[132:135], v[192:195], v[28:31]
	v_mfma_f32_16x16x32_bf16 v[24:27], v[140:143], v[192:195], v[24:27]
	v_mfma_f32_16x16x32_bf16 v[12:15], v[132:135], v[210:213], v[12:15]
	v_mfma_f32_16x16x32_bf16 v[8:11], v[140:143], v[210:213], v[8:11]
	v_mfma_f32_16x16x32_bf16 v[52:55], v[144:147], v[160:163], v[52:55]
	v_mfma_f32_16x16x32_bf16 v[48:51], v[152:155], v[160:163], v[48:51]
	v_mfma_f32_16x16x32_bf16 v[36:39], v[144:147], v[168:171], v[36:39]
	v_mfma_f32_16x16x32_bf16 v[32:35], v[152:155], v[168:171], v[32:35]
	v_mfma_f32_16x16x32_bf16 v[20:23], v[144:147], v[188:191], v[20:23]
	v_mfma_f32_16x16x32_bf16 v[16:19], v[152:155], v[188:191], v[16:19]
	v_mfma_f32_16x16x32_bf16 v[4:7], v[144:147], v[196:199], v[4:7]
	v_mfma_f32_16x16x32_bf16 v[0:3], v[152:155], v[196:199], v[0:3]
	v_mfma_f32_16x16x32_bf16 v[52:55], v[148:151], v[164:167], v[52:55]
	v_mfma_f32_16x16x32_bf16 v[48:51], v[156:159], v[164:167], v[48:51]
	v_mfma_f32_16x16x32_bf16 v[36:39], v[148:151], v[172:175], v[36:39]
	v_mfma_f32_16x16x32_bf16 v[32:35], v[156:159], v[172:175], v[32:35]
	v_mfma_f32_16x16x32_bf16 v[20:23], v[148:151], v[192:195], v[20:23]
	v_mfma_f32_16x16x32_bf16 v[16:19], v[156:159], v[192:195], v[16:19]
	v_mfma_f32_16x16x32_bf16 v[4:7], v[148:151], v[210:213], v[4:7]
	v_mfma_f32_16x16x32_bf16 v[0:3], v[156:159], v[210:213], v[0:3]
	s_barrier
	s_add_i32 s46, 0, 0x18000
	s_add_i32 s47, 0, 0x1c000
	v_add_u32_e32 v140, s46, v204
	v_add_u32_e32 v156, s47, v204
	ds_read_b128 v[128:131], v140
	ds_read_b128 v[132:135], v140 offset:1024
	ds_read_b128 v[136:139], v140 offset:2048
	ds_read_b128 v[140:143], v140 offset:3072
	ds_read_b128 v[144:147], v156
	ds_read_b128 v[148:151], v156 offset:1024
	ds_read_b128 v[152:155], v156 offset:2048
	ds_read_b128 v[156:159], v156 offset:3072
	s_add_u32 s30, s30, 0x80000
	s_addc_u32 s31, s31, 0
	s_mov_b32 m0, s40
	v_lshl_add_u64 v[222:223], s[30:31], 0, v[176:177]
	ds_read_b128 v[160:163], v208 offset:32768
	ds_read_b128 v[164:167], v208 offset:33792
	ds_read_b128 v[168:171], v208 offset:34816
	ds_read_b128 v[172:175], v208 offset:35840
	ds_read_b128 v[188:191], v208 offset:36864
	ds_read_b128 v[192:195], v208 offset:37888
	ds_read_b128 v[196:199], v208 offset:38912
	ds_read_b128 v[210:213], v208 offset:39936
	global_load_lds_dwordx4 v[222:223], off
	s_mov_b32 m0, s41
	v_lshl_add_u64 v[222:223], s[30:31], 0, v[180:181]
	global_load_lds_dwordx4 v[222:223], off
	s_waitcnt vmcnt(8)
	s_waitcnt lgkmcnt(0)
	s_barrier
	s_waitcnt lgkmcnt(0)
	v_mfma_f32_16x16x32_bf16 v[124:127], v[128:131], v[160:163], v[124:127]
	v_mfma_f32_16x16x32_bf16 v[120:123], v[136:139], v[160:163], v[120:123]
	v_mfma_f32_16x16x32_bf16 v[108:111], v[128:131], v[168:171], v[108:111]
	v_mfma_f32_16x16x32_bf16 v[104:107], v[136:139], v[168:171], v[104:107]
	v_mfma_f32_16x16x32_bf16 v[92:95], v[128:131], v[188:191], v[92:95]
	v_mfma_f32_16x16x32_bf16 v[88:91], v[136:139], v[188:191], v[88:91]
	v_mfma_f32_16x16x32_bf16 v[76:79], v[128:131], v[196:199], v[76:79]
	v_mfma_f32_16x16x32_bf16 v[72:75], v[136:139], v[196:199], v[72:75]
	v_mfma_f32_16x16x32_bf16 v[124:127], v[132:135], v[164:167], v[124:127]
	v_mfma_f32_16x16x32_bf16 v[120:123], v[140:143], v[164:167], v[120:123]
	v_mfma_f32_16x16x32_bf16 v[108:111], v[132:135], v[172:175], v[108:111]
	v_mfma_f32_16x16x32_bf16 v[104:107], v[140:143], v[172:175], v[104:107]
	v_mfma_f32_16x16x32_bf16 v[92:95], v[132:135], v[192:195], v[92:95]
	v_mfma_f32_16x16x32_bf16 v[88:91], v[140:143], v[192:195], v[88:91]
	v_mfma_f32_16x16x32_bf16 v[76:79], v[132:135], v[210:213], v[76:79]
	v_mfma_f32_16x16x32_bf16 v[72:75], v[140:143], v[210:213], v[72:75]
	v_mfma_f32_16x16x32_bf16 v[116:119], v[144:147], v[160:163], v[116:119]
	v_mfma_f32_16x16x32_bf16 v[112:115], v[152:155], v[160:163], v[112:115]
	v_mfma_f32_16x16x32_bf16 v[100:103], v[144:147], v[168:171], v[100:103]
	v_mfma_f32_16x16x32_bf16 v[96:99], v[152:155], v[168:171], v[96:99]
	v_mfma_f32_16x16x32_bf16 v[84:87], v[144:147], v[188:191], v[84:87]
	v_mfma_f32_16x16x32_bf16 v[80:83], v[152:155], v[188:191], v[80:83]
	v_mfma_f32_16x16x32_bf16 v[68:71], v[144:147], v[196:199], v[68:71]
	v_mfma_f32_16x16x32_bf16 v[64:67], v[152:155], v[196:199], v[64:67]
	v_mfma_f32_16x16x32_bf16 v[116:119], v[148:151], v[164:167], v[116:119]
	v_mfma_f32_16x16x32_bf16 v[112:115], v[156:159], v[164:167], v[112:115]
	v_mfma_f32_16x16x32_bf16 v[100:103], v[148:151], v[172:175], v[100:103]
	v_mfma_f32_16x16x32_bf16 v[96:99], v[156:159], v[172:175], v[96:99]
	v_mfma_f32_16x16x32_bf16 v[84:87], v[148:151], v[192:195], v[84:87]
	v_mfma_f32_16x16x32_bf16 v[80:83], v[156:159], v[192:195], v[80:83]
	v_mfma_f32_16x16x32_bf16 v[68:71], v[148:151], v[210:213], v[68:71]
	v_mfma_f32_16x16x32_bf16 v[64:67], v[156:159], v[210:213], v[64:67]
	s_barrier
; #define PG8_STAGE(bufoff, gbase, voff) do { _Pragma("unroll") for (int _i = 0; _i < 2; ++_i) \
;         __builtin_amdgcn_global_load_lds((const unsigned*)((const char*)(gbase) + (voff)[_i]), (LAS unsigned*)(lds + (bufoff) + ldsw + _i * 8192), 16, 0, 0); } while (0)
; #define PG8_LDA(dst, b, h) do { _Pragma("unroll") for (int m = 0; m < 4; ++m) _Pragma("unroll") for (int k = 0; k < 2; ++k) dst[m][k] = *(const LAS bf16x8*)(lds + PG8_SA(b, h) + aoff + m * 2048 + k * 1024); } while (0)
; #define PG8_MMA(ai, bj, At, Bt) do { __builtin_amdgcn_s_setprio(1); _Pragma("unroll") for (int m = 0; m < 4; ++m) _Pragma("unroll") for (int n = 0; n < 2; ++n) _Pragma("unroll") for (int k = 0; k < 2; ++k) \
;         acc[ai][bj][m][n] = __builtin_amdgcn_mfma_f32_16x16x32_bf16(Bt[n][k], At[m][k], acc[ai][bj][m][n], 0, 0, 0); __builtin_amdgcn_s_setprio(0); } while (0)
; #define PG8_WAIT_V(n) asm volatile("s_waitcnt vmcnt(" #n ")" ::: "memory")
; #define PG8_WAIT_L(n) asm volatile("s_waitcnt lgkmcnt(" #n ")" ::: "memory")
; #define PG8_BAR __builtin_amdgcn_s_barrier()
; #define PG8_SCHED __builtin_amdgcn_sched_barrier(0)
; template <class Epi, class Sched, bool ALIGN_EPI = true>
; __device__ __forceinline__ void gemm_phase(LAS unsigned char* lds, const Gemm g, const Sched& S, const Epi& E) {
;     ...
;             PG8_LDA(At, 1, 1); PG8_STAGE(PG8_SB(1, 0), b3, voffB); PG8_STAGE(PG8_SB(1, 1), b3 + hstep, voffB); PG8_STAGE(PG8_SA(1, 0), a3, voffA);
;             PG8_WAIT_V(8); PG8_WAIT_L(0); PG8_BAR; PG8_MMA(1, 0, At, B0); PG8_MMA(1, 1, At, B1); PG8_BAR; PG8_SCHED;
;         }
	s_add_i32 s30, s46, s37
	v_lshl_add_u64 v[214:215], v[214:215], 0, s[20:21]
	s_mov_b32 m0, s30
	ds_read_b128 v[160:163], v208 offset:49152
	ds_read_b128 v[164:167], v208 offset:50176
	ds_read_b128 v[168:171], v208 offset:51200
	ds_read_b128 v[172:175], v208 offset:52224
	ds_read_b128 v[188:191], v208 offset:53248
	ds_read_b128 v[192:195], v208 offset:54272
	ds_read_b128 v[196:199], v208 offset:55296
	ds_read_b128 v[210:213], v208 offset:56320
	global_load_lds_dwordx4 v[214:215], off
	s_add_i32 m0, s30, 0x2000
	s_add_u32 s28, s28, 0x80080
	v_lshl_add_u64 v[214:215], v[216:217], 0, s[20:21]
	s_addc_u32 s29, s29, 0
	s_add_i32 s30, s47, s37
	global_load_lds_dwordx4 v[214:215], off
	s_mov_b32 m0, s30
	v_lshl_add_u64 v[214:215], s[28:29], 0, v[178:179]
	global_load_lds_dwordx4 v[214:215], off
	s_add_i32 m0, s30, 0x2000
	v_lshl_add_u64 v[214:215], s[28:29], 0, v[182:183]
	global_load_lds_dwordx4 v[214:215], off
	s_mov_b32 m0, s42
	v_lshl_add_u64 v[214:215], v[218:219], 0, s[20:21]
	global_load_lds_dwordx4 v[214:215], off
	s_mov_b32 m0, s43
	v_lshl_add_u64 v[214:215], v[220:221], 0, s[20:21]
	global_load_lds_dwordx4 v[214:215], off
	s_waitcnt vmcnt(8)
	s_waitcnt lgkmcnt(0)
	s_barrier
	s_waitcnt lgkmcnt(0)
	v_mfma_f32_16x16x32_bf16 v[60:63], v[128:131], v[160:163], v[60:63]
	v_mfma_f32_16x16x32_bf16 v[56:59], v[136:139], v[160:163], v[56:59]
	v_mfma_f32_16x16x32_bf16 v[44:47], v[128:131], v[168:171], v[44:47]
	v_mfma_f32_16x16x32_bf16 v[40:43], v[136:139], v[168:171], v[40:43]
	v_mfma_f32_16x16x32_bf16 v[28:31], v[128:131], v[188:191], v[28:31]
	v_mfma_f32_16x16x32_bf16 v[24:27], v[136:139], v[188:191], v[24:27]
	v_mfma_f32_16x16x32_bf16 v[12:15], v[128:131], v[196:199], v[12:15]
	v_mfma_f32_16x16x32_bf16 v[8:11], v[136:139], v[196:199], v[8:11]
	v_mfma_f32_16x16x32_bf16 v[60:63], v[132:135], v[164:167], v[60:63]
	v_mfma_f32_16x16x32_bf16 v[56:59], v[140:143], v[164:167], v[56:59]
	v_mfma_f32_16x16x32_bf16 v[44:47], v[132:135], v[172:175], v[44:47]
	v_mfma_f32_16x16x32_bf16 v[40:43], v[140:143], v[172:175], v[40:43]
	v_mfma_f32_16x16x32_bf16 v[28:31], v[132:135], v[192:195], v[28:31]
	v_mfma_f32_16x16x32_bf16 v[24:27], v[140:143], v[192:195], v[24:27]
	v_mfma_f32_16x16x32_bf16 v[12:15], v[132:135], v[210:213], v[12:15]
	v_mfma_f32_16x16x32_bf16 v[8:11], v[140:143], v[210:213], v[8:11]
	v_mfma_f32_16x16x32_bf16 v[52:55], v[144:147], v[160:163], v[52:55]
	v_mfma_f32_16x16x32_bf16 v[48:51], v[152:155], v[160:163], v[48:51]
	v_mfma_f32_16x16x32_bf16 v[36:39], v[144:147], v[168:171], v[36:39]
	v_mfma_f32_16x16x32_bf16 v[32:35], v[152:155], v[168:171], v[32:35]
	v_mfma_f32_16x16x32_bf16 v[20:23], v[144:147], v[188:191], v[20:23]
	v_mfma_f32_16x16x32_bf16 v[16:19], v[152:155], v[188:191], v[16:19]
	v_mfma_f32_16x16x32_bf16 v[4:7], v[144:147], v[196:199], v[4:7]
	v_mfma_f32_16x16x32_bf16 v[0:3], v[152:155], v[196:199], v[0:3]
	v_mfma_f32_16x16x32_bf16 v[52:55], v[148:151], v[164:167], v[52:55]
	v_mfma_f32_16x16x32_bf16 v[48:51], v[156:159], v[164:167], v[48:51]
	v_mfma_f32_16x16x32_bf16 v[36:39], v[148:151], v[172:175], v[36:39]
	v_mfma_f32_16x16x32_bf16 v[32:35], v[156:159], v[172:175], v[32:35]
	v_mfma_f32_16x16x32_bf16 v[20:23], v[148:151], v[192:195], v[20:23]
	v_mfma_f32_16x16x32_bf16 v[16:19], v[156:159], v[192:195], v[16:19]
	v_mfma_f32_16x16x32_bf16 v[4:7], v[148:151], v[210:213], v[4:7]
	v_mfma_f32_16x16x32_bf16 v[0:3], v[156:159], v[210:213], v[0:3]
	s_add_i32 s58, s58, 2
	s_add_u32 s26, s26, 0x100
	s_addc_u32 s27, s27, 0
	s_add_u32 s56, s56, 0x100
	s_addc_u32 s57, s57, 0
	s_cmp_gt_u32 s58, 29
	s_barrier
	s_cbranch_scc0 .LBB0_560
	s_and_b64 vcc, exec, s[22:23]
	s_cbranch_vccz .LBB0_563
	s_barrier

; #define PG8_STAGE(bufoff, gbase, voff) do { _Pragma("unroll") for (int _i = 0; _i < 2; ++_i) \
;         __builtin_amdgcn_global_load_lds((const unsigned*)((const char*)(gbase) + (voff)[_i]), (LAS unsigned*)(lds + (bufoff) + ldsw + _i * 8192), 16, 0, 0); } while (0)
; #define PG8_LDA(dst, b, h) do { _Pragma("unroll") for (int m = 0; m < 4; ++m) _Pragma("unroll") for (int k = 0; k < 2; ++k) dst[m][k] = *(const LAS bf16x8*)(lds + PG8_SA(b, h) + aoff + m * 2048 + k * 1024); } while (0)
; #define PG8_LDB(dst, b, h) do { _Pragma("unroll") for (int n = 0; n < 2; ++n) _Pragma("unroll") for (int k = 0; k < 2; ++k) dst[n][k] = *(const LAS bf16x8*)(lds + PG8_SB(b, h) + boff + n * 2048 + k * 1024); } while (0)
; #define PG8_MMA(ai, bj, At, Bt) do { __builtin_amdgcn_s_setprio(1); _Pragma("unroll") for (int m = 0; m < 4; ++m) _Pragma("unroll") for (int n = 0; n < 2; ++n) _Pragma("unroll") for (int k = 0; k < 2; ++k) \
;         acc[ai][bj][m][n] = __builtin_amdgcn_mfma_f32_16x16x32_bf16(Bt[n][k], At[m][k], acc[ai][bj][m][n], 0, 0, 0); __builtin_amdgcn_s_setprio(0); } while (0)
; #define PG8_WAIT_V(n) asm volatile("s_waitcnt vmcnt(" #n ")" ::: "memory")
; #define PG8_WAIT_L(n) asm volatile("s_waitcnt lgkmcnt(" #n ")" ::: "memory")
; #define PG8_BAR __builtin_amdgcn_s_barrier()
; #define PG8_SCHED __builtin_amdgcn_sched_barrier(0)
; template <class Epi, class Sched, bool ALIGN_EPI = true>
; __device__ __forceinline__ void gemm_phase(LAS unsigned char* lds, const Gemm g, const Sched& S, const Epi& E) {
;     ...
;             PG8_LDB(B0, 0, 0); PG8_LDB(B1, 0, 1); PG8_SCHED; PG8_LDA(At, 0, 0); PG8_STAGE(PG8_SA(1, 1), a1 + hstep, voffA);
;             PG8_WAIT_V(8); PG8_WAIT_L(0); PG8_BAR; PG8_MMA(0, 0, At, B0); PG8_MMA(0, 1, At, B1); PG8_BAR; PG8_SCHED;
;             PG8_LDA(At, 0, 1); PG8_STAGE(PG8_SB(0, 0), b2, voffB); PG8_STAGE(PG8_SB(0, 1), b2 + hstep, voffB); PG8_STAGE(PG8_SA(0, 0), a2, voffA);
;             PG8_WAIT_V(8); PG8_WAIT_L(0); PG8_BAR; PG8_MMA(1, 0, At, B0); PG8_MMA(1, 1, At, B1); PG8_BAR; PG8_SCHED;
.LBB0_647:
	ds_read_b128 v[152:155], v147
	ds_read_b128 v[156:159], v147 offset:1024
	ds_read_b128 v[160:163], v147 offset:2048
	ds_read_b128 v[164:167], v147 offset:3072
	ds_read_b128 v[168:171], v148
	ds_read_b128 v[172:175], v148 offset:1024
	ds_read_b128 v[176:179], v148 offset:2048
	ds_read_b128 v[180:183], v148 offset:3072
	s_add_u32 s26, s24, 0xfff80080
	s_addc_u32 s27, s25, -1
	s_cmp_eq_u32 s56, 28
	s_cselect_b32 s29, s51, s27
	s_cselect_b32 s28, s52, s26
	s_cselect_b32 s27, s7, s55
	s_cselect_b32 s26, s53, s54
	v_lshl_add_u64 v[140:141], s[24:25], 0, v[136:137]
	s_add_i32 m0, s37, 0xc000
	ds_read_b128 v[184:187], v149
	ds_read_b128 v[188:191], v149 offset:1024
	ds_read_b128 v[192:195], v149 offset:2048
	ds_read_b128 v[196:199], v149 offset:3072
	ds_read_b128 v[204:207], v149 offset:4096
	ds_read_b128 v[208:211], v149 offset:5120
	ds_read_b128 v[212:215], v149 offset:6144
	ds_read_b128 v[216:219], v149 offset:7168
	global_load_lds_dwordx4 v[140:141], off
	s_add_i32 m0, s37, 0xe000
	v_lshl_add_u64 v[140:141], s[24:25], 0, v[138:139]
	global_load_lds_dwordx4 v[140:141], off
	s_waitcnt vmcnt(8)
	s_waitcnt lgkmcnt(0)
	s_barrier
	s_waitcnt lgkmcnt(0)
	v_mfma_f32_16x16x32_bf16 v[112:115], v[152:155], v[184:187], v[112:115]
	v_mfma_f32_16x16x32_bf16 v[108:111], v[160:163], v[184:187], v[108:111]
	v_mfma_f32_16x16x32_bf16 v[100:103], v[152:155], v[192:195], v[100:103]
	v_mfma_f32_16x16x32_bf16 v[96:99], v[160:163], v[192:195], v[96:99]
	v_mfma_f32_16x16x32_bf16 v[92:95], v[152:155], v[204:207], v[92:95]
	v_mfma_f32_16x16x32_bf16 v[84:87], v[160:163], v[204:207], v[84:87]
	v_mfma_f32_16x16x32_bf16 v[76:79], v[152:155], v[212:215], v[76:79]
	v_mfma_f32_16x16x32_bf16 v[68:71], v[160:163], v[212:215], v[68:71]
	v_mfma_f32_16x16x32_bf16 v[112:115], v[156:159], v[188:191], v[112:115]
	v_mfma_f32_16x16x32_bf16 v[108:111], v[164:167], v[188:191], v[108:111]
	v_mfma_f32_16x16x32_bf16 v[100:103], v[156:159], v[196:199], v[100:103]
	v_mfma_f32_16x16x32_bf16 v[96:99], v[164:167], v[196:199], v[96:99]
	v_mfma_f32_16x16x32_bf16 v[92:95], v[156:159], v[208:211], v[92:95]
	v_mfma_f32_16x16x32_bf16 v[84:87], v[164:167], v[208:211], v[84:87]
	v_mfma_f32_16x16x32_bf16 v[76:79], v[156:159], v[216:219], v[76:79]
	v_mfma_f32_16x16x32_bf16 v[68:71], v[164:167], v[216:219], v[68:71]
	v_mfma_f32_16x16x32_bf16 v[124:127], v[168:171], v[184:187], v[124:127]
	v_mfma_f32_16x16x32_bf16 v[120:123], v[176:179], v[184:187], v[120:123]
	v_mfma_f32_16x16x32_bf16 v[116:119], v[168:171], v[192:195], v[116:119]
	v_mfma_f32_16x16x32_bf16 v[104:107], v[176:179], v[192:195], v[104:107]
	v_mfma_f32_16x16x32_bf16 v[88:91], v[168:171], v[204:207], v[88:91]
	v_mfma_f32_16x16x32_bf16 v[80:83], v[176:179], v[204:207], v[80:83]
	v_mfma_f32_16x16x32_bf16 v[72:75], v[168:171], v[212:215], v[72:75]
	v_mfma_f32_16x16x32_bf16 v[64:67], v[176:179], v[212:215], v[64:67]
	v_mfma_f32_16x16x32_bf16 v[124:127], v[172:175], v[188:191], v[124:127]
	v_mfma_f32_16x16x32_bf16 v[120:123], v[180:183], v[188:191], v[120:123]
	v_mfma_f32_16x16x32_bf16 v[116:119], v[172:175], v[196:199], v[116:119]
	v_mfma_f32_16x16x32_bf16 v[104:107], v[180:183], v[196:199], v[104:107]
	v_mfma_f32_16x16x32_bf16 v[88:91], v[172:175], v[208:211], v[88:91]
	v_mfma_f32_16x16x32_bf16 v[80:83], v[180:183], v[208:211], v[80:83]
	v_mfma_f32_16x16x32_bf16 v[72:75], v[172:175], v[216:219], v[72:75]
	v_mfma_f32_16x16x32_bf16 v[64:67], v[180:183], v[216:219], v[64:67]
	s_barrier
	s_add_i32 s46, s43, s36
	v_lshl_add_u64 v[140:141], s[26:27], 0, v[130:131]
	s_mov_b32 m0, s46
	ds_read_b128 v[184:187], v149 offset:16384
	ds_read_b128 v[188:191], v149 offset:17408
	ds_read_b128 v[192:195], v149 offset:18432
	ds_read_b128 v[196:199], v149 offset:19456
	ds_read_b128 v[204:207], v149 offset:20480
	ds_read_b128 v[208:211], v149 offset:21504
	ds_read_b128 v[212:215], v149 offset:22528
	ds_read_b128 v[216:219], v149 offset:23552
	global_load_lds_dwordx4 v[140:141], off
	s_add_i32 m0, s46, 0x2000
	s_add_u32 s46, s26, 0x80000
	v_lshl_add_u64 v[200:201], s[26:27], 0, v[134:135]
	s_addc_u32 s47, s27, 0
	s_add_i32 s57, s44, s36
	global_load_lds_dwordx4 v[200:201], off
	v_lshl_add_u64 v[220:221], s[46:47], 0, v[130:131]
	s_mov_b32 m0, s57
	v_lshl_add_u64 v[222:223], s[28:29], 0, v[132:133]
	global_load_lds_dwordx4 v[220:221], off
	s_add_i32 m0, s57, 0x2000
	v_lshl_add_u64 v[220:221], s[46:47], 0, v[134:135]
	global_load_lds_dwordx4 v[220:221], off
	s_mov_b32 m0, s37
	v_lshl_add_u64 v[220:221], s[28:29], 0, v[128:129]
	global_load_lds_dwordx4 v[220:221], off
	s_mov_b32 m0, s38
	s_nop 0
	global_load_lds_dwordx4 v[222:223], off
	s_waitcnt vmcnt(8)
	s_waitcnt lgkmcnt(0)
	s_barrier
; #define PG8_STAGE(bufoff, gbase, voff) do { _Pragma("unroll") for (int _i = 0; _i < 2; ++_i) \
;         __builtin_amdgcn_global_load_lds((const unsigned*)((const char*)(gbase) + (voff)[_i]), (LAS unsigned*)(lds + (bufoff) + ldsw + _i * 8192), 16, 0, 0); } while (0)
; #define PG8_LDA(dst, b, h) do { _Pragma("unroll") for (int m = 0; m < 4; ++m) _Pragma("unroll") for (int k = 0; k < 2; ++k) dst[m][k] = *(const LAS bf16x8*)(lds + PG8_SA(b, h) + aoff + m * 2048 + k * 1024); } while (0)
; #define PG8_LDB(dst, b, h) do { _Pragma("unroll") for (int n = 0; n < 2; ++n) _Pragma("unroll") for (int k = 0; k < 2; ++k) dst[n][k] = *(const LAS bf16x8*)(lds + PG8_SB(b, h) + boff + n * 2048 + k * 1024); } while (0)
; #define PG8_MMA(ai, bj, At, Bt) do { __builtin_amdgcn_s_setprio(1); _Pragma("unroll") for (int m = 0; m < 4; ++m) _Pragma("unroll") for (int n = 0; n < 2; ++n) _Pragma("unroll") for (int k = 0; k < 2; ++k) \
;         acc[ai][bj][m][n] = __builtin_amdgcn_mfma_f32_16x16x32_bf16(Bt[n][k], At[m][k], acc[ai][bj][m][n], 0, 0, 0); __builtin_amdgcn_s_setprio(0); } while (0)
; #define PG8_WAIT_V(n) asm volatile("s_waitcnt vmcnt(" #n ")" ::: "memory")
; #define PG8_WAIT_L(n) asm volatile("s_waitcnt lgkmcnt(" #n ")" ::: "memory")
; #define PG8_BAR __builtin_amdgcn_s_barrier()
; #define PG8_SCHED __builtin_amdgcn_sched_barrier(0)
; template <class Epi, class Sched, bool ALIGN_EPI = true>
; __device__ __forceinline__ void gemm_phase(LAS unsigned char* lds, const Gemm g, const Sched& S, const Epi& E) {
;     ...
;             PG8_WAIT_V(8); PG8_WAIT_L(0); PG8_BAR; PG8_MMA(1, 0, At, B0); PG8_MMA(1, 1, At, B1); PG8_BAR; PG8_SCHED;
;             PG8_LDB(B0, 1, 0); PG8_LDB(B1, 1, 1); PG8_SCHED; PG8_LDA(At, 1, 0); PG8_STAGE(PG8_SA(0, 1), a2 + hstep, voffA);
;             PG8_WAIT_V(8); PG8_WAIT_L(0); PG8_BAR; PG8_MMA(0, 0, At, B0); PG8_MMA(0, 1, At, B1); PG8_BAR; PG8_SCHED;
	s_waitcnt lgkmcnt(0)
	v_mfma_f32_16x16x32_bf16 v[60:63], v[152:155], v[184:187], v[60:63]
	v_mfma_f32_16x16x32_bf16 v[52:55], v[160:163], v[184:187], v[52:55]
	v_mfma_f32_16x16x32_bf16 v[44:47], v[152:155], v[192:195], v[44:47]
	v_mfma_f32_16x16x32_bf16 v[36:39], v[160:163], v[192:195], v[36:39]
	v_mfma_f32_16x16x32_bf16 v[28:31], v[152:155], v[204:207], v[28:31]
	v_mfma_f32_16x16x32_bf16 v[20:23], v[160:163], v[204:207], v[20:23]
	v_mfma_f32_16x16x32_bf16 v[12:15], v[152:155], v[212:215], v[12:15]
	v_mfma_f32_16x16x32_bf16 v[4:7], v[160:163], v[212:215], v[4:7]
	v_mfma_f32_16x16x32_bf16 v[60:63], v[156:159], v[188:191], v[60:63]
	v_mfma_f32_16x16x32_bf16 v[52:55], v[164:167], v[188:191], v[52:55]
	v_mfma_f32_16x16x32_bf16 v[44:47], v[156:159], v[196:199], v[44:47]
	v_mfma_f32_16x16x32_bf16 v[36:39], v[164:167], v[196:199], v[36:39]
	v_mfma_f32_16x16x32_bf16 v[28:31], v[156:159], v[208:211], v[28:31]
	v_mfma_f32_16x16x32_bf16 v[20:23], v[164:167], v[208:211], v[20:23]
	v_mfma_f32_16x16x32_bf16 v[12:15], v[156:159], v[216:219], v[12:15]
	v_mfma_f32_16x16x32_bf16 v[4:7], v[164:167], v[216:219], v[4:7]
	v_mfma_f32_16x16x32_bf16 v[56:59], v[168:171], v[184:187], v[56:59]
	v_mfma_f32_16x16x32_bf16 v[48:51], v[176:179], v[184:187], v[48:51]
	v_mfma_f32_16x16x32_bf16 v[40:43], v[168:171], v[192:195], v[40:43]
	v_mfma_f32_16x16x32_bf16 v[32:35], v[176:179], v[192:195], v[32:35]
	v_mfma_f32_16x16x32_bf16 v[24:27], v[168:171], v[204:207], v[24:27]
	v_mfma_f32_16x16x32_bf16 v[16:19], v[176:179], v[204:207], v[16:19]
	v_mfma_f32_16x16x32_bf16 v[8:11], v[168:171], v[212:215], v[8:11]
	v_mfma_f32_16x16x32_bf16 v[0:3], v[176:179], v[212:215], v[0:3]
	v_mfma_f32_16x16x32_bf16 v[56:59], v[172:175], v[188:191], v[56:59]
	v_mfma_f32_16x16x32_bf16 v[48:51], v[180:183], v[188:191], v[48:51]
	v_mfma_f32_16x16x32_bf16 v[40:43], v[172:175], v[196:199], v[40:43]
	v_mfma_f32_16x16x32_bf16 v[32:35], v[180:183], v[196:199], v[32:35]
	v_mfma_f32_16x16x32_bf16 v[24:27], v[172:175], v[208:211], v[24:27]
	v_mfma_f32_16x16x32_bf16 v[16:19], v[180:183], v[208:211], v[16:19]
	v_mfma_f32_16x16x32_bf16 v[8:11], v[172:175], v[216:219], v[8:11]
	v_mfma_f32_16x16x32_bf16 v[0:3], v[180:183], v[216:219], v[0:3]
	s_barrier
	s_add_i32 s46, 0, 0x18000
	v_add_u32_e32 v151, s46, v145
	s_add_i32 s47, 0, 0x1c000
	ds_read_b128 v[152:155], v151
	ds_read_b128 v[156:159], v151 offset:1024
	ds_read_b128 v[160:163], v151 offset:2048
	ds_read_b128 v[164:167], v151 offset:3072
	v_add_u32_e32 v151, s47, v145
	ds_read_b128 v[168:171], v151
	ds_read_b128 v[172:175], v151 offset:1024
	ds_read_b128 v[176:179], v151 offset:2048
	ds_read_b128 v[180:183], v151 offset:3072
	s_add_u32 s28, s28, 0x80000
	s_addc_u32 s29, s29, 0
	s_mov_b32 m0, s39
	v_lshl_add_u64 v[224:225], s[28:29], 0, v[128:129]
	ds_read_b128 v[184:187], v149 offset:32768
	ds_read_b128 v[188:191], v149 offset:33792
	ds_read_b128 v[192:195], v149 offset:34816
	ds_read_b128 v[196:199], v149 offset:35840
	ds_read_b128 v[204:207], v149 offset:36864
	ds_read_b128 v[208:211], v149 offset:37888
	ds_read_b128 v[212:215], v149 offset:38912
	ds_read_b128 v[216:219], v149 offset:39936
	global_load_lds_dwordx4 v[224:225], off
	s_mov_b32 m0, s40
	v_lshl_add_u64 v[224:225], s[28:29], 0, v[132:133]
	global_load_lds_dwordx4 v[224:225], off
	s_waitcnt vmcnt(8)
	s_waitcnt lgkmcnt(0)
	s_barrier
	s_waitcnt lgkmcnt(0)
	v_mfma_f32_16x16x32_bf16 v[112:115], v[152:155], v[184:187], v[112:115]
	v_mfma_f32_16x16x32_bf16 v[108:111], v[160:163], v[184:187], v[108:111]
	v_mfma_f32_16x16x32_bf16 v[100:103], v[152:155], v[192:195], v[100:103]
	v_mfma_f32_16x16x32_bf16 v[96:99], v[160:163], v[192:195], v[96:99]
	v_mfma_f32_16x16x32_bf16 v[92:95], v[152:155], v[204:207], v[92:95]
	v_mfma_f32_16x16x32_bf16 v[84:87], v[160:163], v[204:207], v[84:87]
	v_mfma_f32_16x16x32_bf16 v[76:79], v[152:155], v[212:215], v[76:79]
	v_mfma_f32_16x16x32_bf16 v[68:71], v[160:163], v[212:215], v[68:71]
	v_mfma_f32_16x16x32_bf16 v[112:115], v[156:159], v[188:191], v[112:115]
	v_mfma_f32_16x16x32_bf16 v[108:111], v[164:167], v[188:191], v[108:111]
	v_mfma_f32_16x16x32_bf16 v[100:103], v[156:159], v[196:199], v[100:103]
	v_mfma_f32_16x16x32_bf16 v[96:99], v[164:167], v[196:199], v[96:99]
	v_mfma_f32_16x16x32_bf16 v[92:95], v[156:159], v[208:211], v[92:95]
	v_mfma_f32_16x16x32_bf16 v[84:87], v[164:167], v[208:211], v[84:87]
	v_mfma_f32_16x16x32_bf16 v[76:79], v[156:159], v[216:219], v[76:79]
	v_mfma_f32_16x16x32_bf16 v[68:71], v[164:167], v[216:219], v[68:71]
	v_mfma_f32_16x16x32_bf16 v[124:127], v[168:171], v[184:187], v[124:127]
	v_mfma_f32_16x16x32_bf16 v[120:123], v[176:179], v[184:187], v[120:123]
	v_mfma_f32_16x16x32_bf16 v[116:119], v[168:171], v[192:195], v[116:119]
	v_mfma_f32_16x16x32_bf16 v[104:107], v[176:179], v[192:195], v[104:107]
	v_mfma_f32_16x16x32_bf16 v[88:91], v[168:171], v[204:207], v[88:91]
	v_mfma_f32_16x16x32_bf16 v[80:83], v[176:179], v[204:207], v[80:83]
	v_mfma_f32_16x16x32_bf16 v[72:75], v[168:171], v[212:215], v[72:75]
	v_mfma_f32_16x16x32_bf16 v[64:67], v[176:179], v[212:215], v[64:67]
	v_mfma_f32_16x16x32_bf16 v[124:127], v[172:175], v[188:191], v[124:127]
	v_mfma_f32_16x16x32_bf16 v[120:123], v[180:183], v[188:191], v[120:123]
	v_mfma_f32_16x16x32_bf16 v[116:119], v[172:175], v[196:199], v[116:119]
	v_mfma_f32_16x16x32_bf16 v[104:107], v[180:183], v[196:199], v[104:107]
	v_mfma_f32_16x16x32_bf16 v[88:91], v[172:175], v[208:211], v[88:91]
	v_mfma_f32_16x16x32_bf16 v[80:83], v[180:183], v[208:211], v[80:83]
	v_mfma_f32_16x16x32_bf16 v[72:75], v[172:175], v[216:219], v[72:75]
	v_mfma_f32_16x16x32_bf16 v[64:67], v[180:183], v[216:219], v[64:67]
	s_barrier
; #define PG8_STAGE(bufoff, gbase, voff) do { _Pragma("unroll") for (int _i = 0; _i < 2; ++_i) \
;         __builtin_amdgcn_global_load_lds((const unsigned*)((const char*)(gbase) + (voff)[_i]), (LAS unsigned*)(lds + (bufoff) + ldsw + _i * 8192), 16, 0, 0); } while (0)
; #define PG8_LDA(dst, b, h) do { _Pragma("unroll") for (int m = 0; m < 4; ++m) _Pragma("unroll") for (int k = 0; k < 2; ++k) dst[m][k] = *(const LAS bf16x8*)(lds + PG8_SA(b, h) + aoff + m * 2048 + k * 1024); } while (0)
; #define PG8_MMA(ai, bj, At, Bt) do { __builtin_amdgcn_s_setprio(1); _Pragma("unroll") for (int m = 0; m < 4; ++m) _Pragma("unroll") for (int n = 0; n < 2; ++n) _Pragma("unroll") for (int k = 0; k < 2; ++k) \
;         acc[ai][bj][m][n] = __builtin_amdgcn_mfma_f32_16x16x32_bf16(Bt[n][k], At[m][k], acc[ai][bj][m][n], 0, 0, 0); __builtin_amdgcn_s_setprio(0); } while (0)
; #define PG8_WAIT_V(n) asm volatile("s_waitcnt vmcnt(" #n ")" ::: "memory")
; #define PG8_WAIT_L(n) asm volatile("s_waitcnt lgkmcnt(" #n ")" ::: "memory")
; #define PG8_BAR __builtin_amdgcn_s_barrier()
; #define PG8_SCHED __builtin_amdgcn_sched_barrier(0)
; template <class Epi, class Sched, bool ALIGN_EPI = true>
; __device__ __forceinline__ void gemm_phase(LAS unsigned char* lds, const Gemm g, const Sched& S, const Epi& E) {
;     ...
;             PG8_LDA(At, 1, 1); PG8_STAGE(PG8_SB(1, 0), b3, voffB); PG8_STAGE(PG8_SB(1, 1), b3 + hstep, voffB); PG8_STAGE(PG8_SA(1, 0), a3, voffA);
;             PG8_WAIT_V(8); PG8_WAIT_L(0); PG8_BAR; PG8_MMA(1, 0, At, B0); PG8_MMA(1, 1, At, B1); PG8_BAR; PG8_SCHED;
;         }
	s_add_i32 s28, s46, s36
	v_lshl_add_u64 v[140:141], v[140:141], 0, s[18:19]
	s_mov_b32 m0, s28
	ds_read_b128 v[184:187], v149 offset:49152
	ds_read_b128 v[188:191], v149 offset:50176
	ds_read_b128 v[192:195], v149 offset:51200
	ds_read_b128 v[196:199], v149 offset:52224
	ds_read_b128 v[204:207], v149 offset:53248
	ds_read_b128 v[208:211], v149 offset:54272
	ds_read_b128 v[212:215], v149 offset:55296
	ds_read_b128 v[216:219], v149 offset:56320
	global_load_lds_dwordx4 v[140:141], off
	s_add_i32 m0, s28, 0x2000
	s_add_u32 s26, s26, 0x80080
	v_lshl_add_u64 v[140:141], v[200:201], 0, s[18:19]
	s_addc_u32 s27, s27, 0
	s_add_i32 s28, s47, s36
	global_load_lds_dwordx4 v[140:141], off
	s_mov_b32 m0, s28
	v_lshl_add_u64 v[140:141], s[26:27], 0, v[130:131]
	global_load_lds_dwordx4 v[140:141], off
	s_add_i32 m0, s28, 0x2000
	v_lshl_add_u64 v[140:141], s[26:27], 0, v[134:135]
	global_load_lds_dwordx4 v[140:141], off
	s_mov_b32 m0, s41
	v_lshl_add_u64 v[140:141], v[220:221], 0, s[18:19]
	global_load_lds_dwordx4 v[140:141], off
	s_mov_b32 m0, s42
	v_lshl_add_u64 v[140:141], v[222:223], 0, s[18:19]
	global_load_lds_dwordx4 v[140:141], off
	s_waitcnt vmcnt(8)
	s_waitcnt lgkmcnt(0)
	s_barrier
	s_waitcnt lgkmcnt(0)
	v_mfma_f32_16x16x32_bf16 v[60:63], v[152:155], v[184:187], v[60:63]
	v_mfma_f32_16x16x32_bf16 v[52:55], v[160:163], v[184:187], v[52:55]
	v_mfma_f32_16x16x32_bf16 v[44:47], v[152:155], v[192:195], v[44:47]
	v_mfma_f32_16x16x32_bf16 v[36:39], v[160:163], v[192:195], v[36:39]
	v_mfma_f32_16x16x32_bf16 v[28:31], v[152:155], v[204:207], v[28:31]
	v_mfma_f32_16x16x32_bf16 v[20:23], v[160:163], v[204:207], v[20:23]
	v_mfma_f32_16x16x32_bf16 v[12:15], v[152:155], v[212:215], v[12:15]
	v_mfma_f32_16x16x32_bf16 v[4:7], v[160:163], v[212:215], v[4:7]
	v_mfma_f32_16x16x32_bf16 v[60:63], v[156:159], v[188:191], v[60:63]
	v_mfma_f32_16x16x32_bf16 v[52:55], v[164:167], v[188:191], v[52:55]
	v_mfma_f32_16x16x32_bf16 v[44:47], v[156:159], v[196:199], v[44:47]
	v_mfma_f32_16x16x32_bf16 v[36:39], v[164:167], v[196:199], v[36:39]
	v_mfma_f32_16x16x32_bf16 v[28:31], v[156:159], v[208:211], v[28:31]
	v_mfma_f32_16x16x32_bf16 v[20:23], v[164:167], v[208:211], v[20:23]
	v_mfma_f32_16x16x32_bf16 v[12:15], v[156:159], v[216:219], v[12:15]
	v_mfma_f32_16x16x32_bf16 v[4:7], v[164:167], v[216:219], v[4:7]
	v_mfma_f32_16x16x32_bf16 v[56:59], v[168:171], v[184:187], v[56:59]
	v_mfma_f32_16x16x32_bf16 v[48:51], v[176:179], v[184:187], v[48:51]
	v_mfma_f32_16x16x32_bf16 v[40:43], v[168:171], v[192:195], v[40:43]
	v_mfma_f32_16x16x32_bf16 v[32:35], v[176:179], v[192:195], v[32:35]
	v_mfma_f32_16x16x32_bf16 v[24:27], v[168:171], v[204:207], v[24:27]
	v_mfma_f32_16x16x32_bf16 v[16:19], v[176:179], v[204:207], v[16:19]
	v_mfma_f32_16x16x32_bf16 v[8:11], v[168:171], v[212:215], v[8:11]
	v_mfma_f32_16x16x32_bf16 v[0:3], v[176:179], v[212:215], v[0:3]
	v_mfma_f32_16x16x32_bf16 v[56:59], v[172:175], v[188:191], v[56:59]
	v_mfma_f32_16x16x32_bf16 v[48:51], v[180:183], v[188:191], v[48:51]
	v_mfma_f32_16x16x32_bf16 v[40:43], v[172:175], v[196:199], v[40:43]
	v_mfma_f32_16x16x32_bf16 v[32:35], v[180:183], v[196:199], v[32:35]
	v_mfma_f32_16x16x32_bf16 v[24:27], v[172:175], v[208:211], v[24:27]
	v_mfma_f32_16x16x32_bf16 v[16:19], v[180:183], v[208:211], v[16:19]
	v_mfma_f32_16x16x32_bf16 v[8:11], v[172:175], v[216:219], v[8:11]
	v_mfma_f32_16x16x32_bf16 v[0:3], v[180:183], v[216:219], v[0:3]
	s_add_i32 s56, s56, 2
	s_add_u32 s24, s24, 0x100
	s_addc_u32 s25, s25, 0
	s_add_u32 s54, s54, 0x100
	s_addc_u32 s55, s55, 0
	s_cmp_gt_u32 s56, 29
	s_barrier
	s_cbranch_scc0 .LBB0_647
	s_and_b64 vcc, exec, s[20:21]
	s_cbranch_vccz .LBB0_650
	s_barrier

; #define PG8_STAGE(bufoff, gbase, voff) do { _Pragma("unroll") for (int _i = 0; _i < 2; ++_i) \
;         __builtin_amdgcn_global_load_lds((const unsigned*)((const char*)(gbase) + (voff)[_i]), (LAS unsigned*)(lds + (bufoff) + ldsw + _i * 8192), 16, 0, 0); } while (0)
; #define PG8_LDA(dst, b, h) do { _Pragma("unroll") for (int m = 0; m < 4; ++m) _Pragma("unroll") for (int k = 0; k < 2; ++k) dst[m][k] = *(const LAS bf16x8*)(lds + PG8_SA(b, h) + aoff + m * 2048 + k * 1024); } while (0)
; #define PG8_LDB(dst, b, h) do { _Pragma("unroll") for (int n = 0; n < 2; ++n) _Pragma("unroll") for (int k = 0; k < 2; ++k) dst[n][k] = *(const LAS bf16x8*)(lds + PG8_SB(b, h) + boff + n * 2048 + k * 1024); } while (0)
; #define PG8_MMA(ai, bj, At, Bt) do { __builtin_amdgcn_s_setprio(1); _Pragma("unroll") for (int m = 0; m < 4; ++m) _Pragma("unroll") for (int n = 0; n < 2; ++n) _Pragma("unroll") for (int k = 0; k < 2; ++k) \
;         acc[ai][bj][m][n] = __builtin_amdgcn_mfma_f32_16x16x32_bf16(Bt[n][k], At[m][k], acc[ai][bj][m][n], 0, 0, 0); __builtin_amdgcn_s_setprio(0); } while (0)
; #define PG8_WAIT_V(n) asm volatile("s_waitcnt vmcnt(" #n ")" ::: "memory")
; #define PG8_WAIT_L(n) asm volatile("s_waitcnt lgkmcnt(" #n ")" ::: "memory")
; #define PG8_BAR __builtin_amdgcn_s_barrier()
; #define PG8_SCHED __builtin_amdgcn_sched_barrier(0)
; template <class Epi, class Sched, bool ALIGN_EPI = true>
; __device__ __forceinline__ void gemm_phase(LAS unsigned char* lds, const Gemm g, const Sched& S, const Epi& E) {
;     ...
;             const char* a1 = cA + (size_t)(t + 1) * kstep;
;             const char* a2 = last ? nA : cA + (size_t)(t + 2) * kstep; const char* b2 = last ? nB : cB + (size_t)(t + 2) * kstep;
;             const char* a3 = a2 + kstep; const char* b3 = b2 + kstep;
;             PG8_LDB(B0, 0, 0); PG8_LDB(B1, 0, 1); PG8_SCHED; PG8_LDA(At, 0, 0); PG8_STAGE(PG8_SA(1, 1), a1 + hstep, voffA);
;             PG8_WAIT_V(8); PG8_WAIT_L(0); PG8_BAR; PG8_MMA(0, 0, At, B0); PG8_MMA(0, 1, At, B1); PG8_BAR; PG8_SCHED;
;             PG8_LDA(At, 0, 1); PG8_STAGE(PG8_SB(0, 0), b2, voffB); PG8_STAGE(PG8_SB(0, 1), b2 + hstep, voffB); PG8_STAGE(PG8_SA(0, 0), a2, voffA);
.LBB0_746:
	ds_read_b128 v[128:131], v187
	ds_read_b128 v[132:135], v187 offset:1024
	ds_read_b128 v[136:139], v187 offset:2048
	ds_read_b128 v[140:143], v187 offset:3072
	ds_read_b128 v[144:147], v188
	ds_read_b128 v[148:151], v188 offset:1024
	ds_read_b128 v[164:167], v188 offset:2048
	ds_read_b128 v[168:171], v188 offset:3072
	s_add_u32 s24, s22, 0x100
	s_addc_u32 s25, s23, 0
	s_cmpk_eq_i32 s56, 0x54
	s_cselect_b32 s29, s19, s25
	s_cselect_b32 s28, s18, s24
	s_cselect_b32 s27, s21, s55
	s_cselect_b32 s26, s20, s54
	s_mov_b32 m0, s43
	v_lshl_add_u64 v[180:181], s[22:23], 0, v[160:161]
	ds_read_b128 v[172:175], v189
	ds_read_b128 v[176:179], v189 offset:1024
	ds_read_b128 v[192:195], v189 offset:2048
	ds_read_b128 v[196:199], v189 offset:3072
	ds_read_b128 v[204:207], v189 offset:4096
	ds_read_b128 v[208:211], v189 offset:5120
	ds_read_b128 v[212:215], v189 offset:6144
	ds_read_b128 v[216:219], v189 offset:7168
	global_load_lds_dwordx4 v[180:181], off
	s_mov_b32 m0, s44
	v_lshl_add_u64 v[180:181], s[22:23], 0, v[162:163]
	global_load_lds_dwordx4 v[180:181], off
	s_waitcnt vmcnt(8)
	s_waitcnt lgkmcnt(0)
	s_barrier
	s_waitcnt lgkmcnt(0)
	v_mfma_f32_16x16x32_bf16 v[124:127], v[128:131], v[172:175], v[124:127]
	v_mfma_f32_16x16x32_bf16 v[120:123], v[136:139], v[172:175], v[120:123]
	v_mfma_f32_16x16x32_bf16 v[108:111], v[128:131], v[192:195], v[108:111]
	v_mfma_f32_16x16x32_bf16 v[104:107], v[136:139], v[192:195], v[104:107]
	v_mfma_f32_16x16x32_bf16 v[92:95], v[128:131], v[204:207], v[92:95]
	v_mfma_f32_16x16x32_bf16 v[88:91], v[136:139], v[204:207], v[88:91]
	v_mfma_f32_16x16x32_bf16 v[76:79], v[128:131], v[212:215], v[76:79]
	v_mfma_f32_16x16x32_bf16 v[72:75], v[136:139], v[212:215], v[72:75]
	v_mfma_f32_16x16x32_bf16 v[124:127], v[132:135], v[176:179], v[124:127]
	v_mfma_f32_16x16x32_bf16 v[120:123], v[140:143], v[176:179], v[120:123]
	v_mfma_f32_16x16x32_bf16 v[108:111], v[132:135], v[196:199], v[108:111]
	v_mfma_f32_16x16x32_bf16 v[104:107], v[140:143], v[196:199], v[104:107]
	v_mfma_f32_16x16x32_bf16 v[92:95], v[132:135], v[208:211], v[92:95]
	v_mfma_f32_16x16x32_bf16 v[88:91], v[140:143], v[208:211], v[88:91]
	v_mfma_f32_16x16x32_bf16 v[76:79], v[132:135], v[216:219], v[76:79]
	v_mfma_f32_16x16x32_bf16 v[72:75], v[140:143], v[216:219], v[72:75]
	v_mfma_f32_16x16x32_bf16 v[116:119], v[144:147], v[172:175], v[116:119]
	v_mfma_f32_16x16x32_bf16 v[112:115], v[164:167], v[172:175], v[112:115]
	v_mfma_f32_16x16x32_bf16 v[100:103], v[144:147], v[192:195], v[100:103]
	v_mfma_f32_16x16x32_bf16 v[96:99], v[164:167], v[192:195], v[96:99]
	v_mfma_f32_16x16x32_bf16 v[84:87], v[144:147], v[204:207], v[84:87]
	v_mfma_f32_16x16x32_bf16 v[80:83], v[164:167], v[204:207], v[80:83]
	v_mfma_f32_16x16x32_bf16 v[68:71], v[144:147], v[212:215], v[68:71]
	v_mfma_f32_16x16x32_bf16 v[64:67], v[164:167], v[212:215], v[64:67]
	v_mfma_f32_16x16x32_bf16 v[116:119], v[148:151], v[176:179], v[116:119]
	v_mfma_f32_16x16x32_bf16 v[112:115], v[168:171], v[176:179], v[112:115]
	v_mfma_f32_16x16x32_bf16 v[100:103], v[148:151], v[196:199], v[100:103]
	v_mfma_f32_16x16x32_bf16 v[96:99], v[168:171], v[196:199], v[96:99]
	v_mfma_f32_16x16x32_bf16 v[84:87], v[148:151], v[208:211], v[84:87]
	v_mfma_f32_16x16x32_bf16 v[80:83], v[168:171], v[208:211], v[80:83]
	v_mfma_f32_16x16x32_bf16 v[68:71], v[148:151], v[216:219], v[68:71]
	v_mfma_f32_16x16x32_bf16 v[64:67], v[168:171], v[216:219], v[64:67]
	s_barrier
	s_mov_b32 m0, s45
	v_lshl_add_u64 v[180:181], s[26:27], 0, v[154:155]
	s_add_u32 s22, s26, 0x160000
	ds_read_b128 v[172:175], v189 offset:16384
	ds_read_b128 v[176:179], v189 offset:17408
	ds_read_b128 v[192:195], v189 offset:18432
	ds_read_b128 v[196:199], v189 offset:19456
	ds_read_b128 v[204:207], v189 offset:20480
	ds_read_b128 v[208:211], v189 offset:21504
	ds_read_b128 v[212:215], v189 offset:22528
	ds_read_b128 v[216:219], v189 offset:23552
	global_load_lds_dwordx4 v[180:181], off
	v_lshl_add_u64 v[200:201], s[26:27], 0, v[158:159]
	s_mov_b32 m0, s48
	s_addc_u32 s23, s27, 0
	global_load_lds_dwordx4 v[200:201], off
	v_lshl_add_u64 v[202:203], s[22:23], 0, v[154:155]
	s_mov_b32 m0, s49
	v_lshl_add_u64 v[220:221], s[28:29], 0, v[156:157]
	global_load_lds_dwordx4 v[202:203], off
	s_add_i32 m0, s49, 0x2000
	v_lshl_add_u64 v[202:203], s[22:23], 0, v[158:159]
	global_load_lds_dwordx4 v[202:203], off
	s_mov_b32 m0, s36
	v_lshl_add_u64 v[202:203], s[28:29], 0, v[152:153]
	global_load_lds_dwordx4 v[202:203], off
	s_mov_b32 m0, s37
	s_nop 0
	global_load_lds_dwordx4 v[220:221], off
	s_waitcnt vmcnt(8)
	s_waitcnt lgkmcnt(0)
	s_barrier
; #define PG8_STAGE(bufoff, gbase, voff) do { _Pragma("unroll") for (int _i = 0; _i < 2; ++_i) \
;         __builtin_amdgcn_global_load_lds((const unsigned*)((const char*)(gbase) + (voff)[_i]), (LAS unsigned*)(lds + (bufoff) + ldsw + _i * 8192), 16, 0, 0); } while (0)
; #define PG8_LDA(dst, b, h) do { _Pragma("unroll") for (int m = 0; m < 4; ++m) _Pragma("unroll") for (int k = 0; k < 2; ++k) dst[m][k] = *(const LAS bf16x8*)(lds + PG8_SA(b, h) + aoff + m * 2048 + k * 1024); } while (0)
; #define PG8_LDB(dst, b, h) do { _Pragma("unroll") for (int n = 0; n < 2; ++n) _Pragma("unroll") for (int k = 0; k < 2; ++k) dst[n][k] = *(const LAS bf16x8*)(lds + PG8_SB(b, h) + boff + n * 2048 + k * 1024); } while (0)
; #define PG8_MMA(ai, bj, At, Bt) do { __builtin_amdgcn_s_setprio(1); _Pragma("unroll") for (int m = 0; m < 4; ++m) _Pragma("unroll") for (int n = 0; n < 2; ++n) _Pragma("unroll") for (int k = 0; k < 2; ++k) \
;         acc[ai][bj][m][n] = __builtin_amdgcn_mfma_f32_16x16x32_bf16(Bt[n][k], At[m][k], acc[ai][bj][m][n], 0, 0, 0); __builtin_amdgcn_s_setprio(0); } while (0)
; #define PG8_WAIT_V(n) asm volatile("s_waitcnt vmcnt(" #n ")" ::: "memory")
; #define PG8_WAIT_L(n) asm volatile("s_waitcnt lgkmcnt(" #n ")" ::: "memory")
; #define PG8_BAR __builtin_amdgcn_s_barrier()
; #define PG8_SCHED __builtin_amdgcn_sched_barrier(0)
; template <class Epi, class Sched, bool ALIGN_EPI = true>
; __device__ __forceinline__ void gemm_phase(LAS unsigned char* lds, const Gemm g, const Sched& S, const Epi& E) {
;     ...
;             PG8_WAIT_V(8); PG8_WAIT_L(0); PG8_BAR; PG8_MMA(1, 0, At, B0); PG8_MMA(1, 1, At, B1); PG8_BAR; PG8_SCHED;
;             PG8_LDB(B0, 1, 0); PG8_LDB(B1, 1, 1); PG8_SCHED; PG8_LDA(At, 1, 0); PG8_STAGE(PG8_SA(0, 1), a2 + hstep, voffA);
;             PG8_WAIT_V(8); PG8_WAIT_L(0); PG8_BAR; PG8_MMA(0, 0, At, B0); PG8_MMA(0, 1, At, B1); PG8_BAR; PG8_SCHED;
;             PG8_LDA(At, 1, 1); PG8_STAGE(PG8_SB(1, 0), b3, voffB); PG8_STAGE(PG8_SB(1, 1), b3 + hstep, voffB); PG8_STAGE(PG8_SA(1, 0), a3, voffA);
	s_waitcnt lgkmcnt(0)
	v_mfma_f32_16x16x32_bf16 v[60:63], v[128:131], v[172:175], v[60:63]
	v_mfma_f32_16x16x32_bf16 v[56:59], v[136:139], v[172:175], v[56:59]
	v_mfma_f32_16x16x32_bf16 v[44:47], v[128:131], v[192:195], v[44:47]
	v_mfma_f32_16x16x32_bf16 v[40:43], v[136:139], v[192:195], v[40:43]
	v_mfma_f32_16x16x32_bf16 v[28:31], v[128:131], v[204:207], v[28:31]
	v_mfma_f32_16x16x32_bf16 v[24:27], v[136:139], v[204:207], v[24:27]
	v_mfma_f32_16x16x32_bf16 v[12:15], v[128:131], v[212:215], v[12:15]
	v_mfma_f32_16x16x32_bf16 v[8:11], v[136:139], v[212:215], v[8:11]
	v_mfma_f32_16x16x32_bf16 v[60:63], v[132:135], v[176:179], v[60:63]
	v_mfma_f32_16x16x32_bf16 v[56:59], v[140:143], v[176:179], v[56:59]
	v_mfma_f32_16x16x32_bf16 v[44:47], v[132:135], v[196:199], v[44:47]
	v_mfma_f32_16x16x32_bf16 v[40:43], v[140:143], v[196:199], v[40:43]
	v_mfma_f32_16x16x32_bf16 v[28:31], v[132:135], v[208:211], v[28:31]
	v_mfma_f32_16x16x32_bf16 v[24:27], v[140:143], v[208:211], v[24:27]
	v_mfma_f32_16x16x32_bf16 v[12:15], v[132:135], v[216:219], v[12:15]
	v_mfma_f32_16x16x32_bf16 v[8:11], v[140:143], v[216:219], v[8:11]
	v_mfma_f32_16x16x32_bf16 v[52:55], v[144:147], v[172:175], v[52:55]
	v_mfma_f32_16x16x32_bf16 v[48:51], v[164:167], v[172:175], v[48:51]
	v_mfma_f32_16x16x32_bf16 v[36:39], v[144:147], v[192:195], v[36:39]
	v_mfma_f32_16x16x32_bf16 v[32:35], v[164:167], v[192:195], v[32:35]
	v_mfma_f32_16x16x32_bf16 v[20:23], v[144:147], v[204:207], v[20:23]
	v_mfma_f32_16x16x32_bf16 v[16:19], v[164:167], v[204:207], v[16:19]
	v_mfma_f32_16x16x32_bf16 v[4:7], v[144:147], v[212:215], v[4:7]
	v_mfma_f32_16x16x32_bf16 v[0:3], v[164:167], v[212:215], v[0:3]
	v_mfma_f32_16x16x32_bf16 v[52:55], v[148:151], v[176:179], v[52:55]
	v_mfma_f32_16x16x32_bf16 v[48:51], v[168:171], v[176:179], v[48:51]
	v_mfma_f32_16x16x32_bf16 v[36:39], v[148:151], v[196:199], v[36:39]
	v_mfma_f32_16x16x32_bf16 v[32:35], v[168:171], v[196:199], v[32:35]
	v_mfma_f32_16x16x32_bf16 v[20:23], v[148:151], v[208:211], v[20:23]
	v_mfma_f32_16x16x32_bf16 v[16:19], v[168:171], v[208:211], v[16:19]
	v_mfma_f32_16x16x32_bf16 v[4:7], v[148:151], v[216:219], v[4:7]
	v_mfma_f32_16x16x32_bf16 v[0:3], v[168:171], v[216:219], v[0:3]
	s_barrier
	s_add_i32 s46, 0, 0x18000
	s_add_i32 s47, 0, 0x1c000
	v_add_u32_e32 v140, s46, v185
	v_add_u32_e32 v168, s47, v185
	ds_read_b128 v[128:131], v140
	ds_read_b128 v[132:135], v140 offset:1024
	ds_read_b128 v[136:139], v140 offset:2048
	ds_read_b128 v[140:143], v140 offset:3072
	ds_read_b128 v[144:147], v168
	ds_read_b128 v[148:151], v168 offset:1024
	ds_read_b128 v[164:167], v168 offset:2048
	ds_read_b128 v[168:171], v168 offset:3072
	s_add_u32 s22, s28, 0x160000
	s_addc_u32 s23, s29, 0
	s_mov_b32 m0, s38
	v_lshl_add_u64 v[222:223], s[22:23], 0, v[152:153]
	ds_read_b128 v[172:175], v189 offset:32768
	ds_read_b128 v[176:179], v189 offset:33792
	ds_read_b128 v[192:195], v189 offset:34816
	ds_read_b128 v[196:199], v189 offset:35840
	ds_read_b128 v[204:207], v189 offset:36864
	ds_read_b128 v[208:211], v189 offset:37888
	ds_read_b128 v[212:215], v189 offset:38912
	ds_read_b128 v[216:219], v189 offset:39936
	global_load_lds_dwordx4 v[222:223], off
	s_mov_b32 m0, s39
	v_lshl_add_u64 v[222:223], s[22:23], 0, v[156:157]
	global_load_lds_dwordx4 v[222:223], off
	s_waitcnt vmcnt(8)
	s_waitcnt lgkmcnt(0)
	s_barrier
	s_waitcnt lgkmcnt(0)
	v_mfma_f32_16x16x32_bf16 v[124:127], v[128:131], v[172:175], v[124:127]
	v_mfma_f32_16x16x32_bf16 v[120:123], v[136:139], v[172:175], v[120:123]
	v_mfma_f32_16x16x32_bf16 v[108:111], v[128:131], v[192:195], v[108:111]
	v_mfma_f32_16x16x32_bf16 v[104:107], v[136:139], v[192:195], v[104:107]
	v_mfma_f32_16x16x32_bf16 v[92:95], v[128:131], v[204:207], v[92:95]
	v_mfma_f32_16x16x32_bf16 v[88:91], v[136:139], v[204:207], v[88:91]
	v_mfma_f32_16x16x32_bf16 v[76:79], v[128:131], v[212:215], v[76:79]
	v_mfma_f32_16x16x32_bf16 v[72:75], v[136:139], v[212:215], v[72:75]
	v_mfma_f32_16x16x32_bf16 v[124:127], v[132:135], v[176:179], v[124:127]
	v_mfma_f32_16x16x32_bf16 v[120:123], v[140:143], v[176:179], v[120:123]
	v_mfma_f32_16x16x32_bf16 v[108:111], v[132:135], v[196:199], v[108:111]
	v_mfma_f32_16x16x32_bf16 v[104:107], v[140:143], v[196:199], v[104:107]
	v_mfma_f32_16x16x32_bf16 v[92:95], v[132:135], v[208:211], v[92:95]
	v_mfma_f32_16x16x32_bf16 v[88:91], v[140:143], v[208:211], v[88:91]
	v_mfma_f32_16x16x32_bf16 v[76:79], v[132:135], v[216:219], v[76:79]
	v_mfma_f32_16x16x32_bf16 v[72:75], v[140:143], v[216:219], v[72:75]
	v_mfma_f32_16x16x32_bf16 v[116:119], v[144:147], v[172:175], v[116:119]
	v_mfma_f32_16x16x32_bf16 v[112:115], v[164:167], v[172:175], v[112:115]
	v_mfma_f32_16x16x32_bf16 v[100:103], v[144:147], v[192:195], v[100:103]
	v_mfma_f32_16x16x32_bf16 v[96:99], v[164:167], v[192:195], v[96:99]
	v_mfma_f32_16x16x32_bf16 v[84:87], v[144:147], v[204:207], v[84:87]
	v_mfma_f32_16x16x32_bf16 v[80:83], v[164:167], v[204:207], v[80:83]
	v_mfma_f32_16x16x32_bf16 v[68:71], v[144:147], v[212:215], v[68:71]
	v_mfma_f32_16x16x32_bf16 v[64:67], v[164:167], v[212:215], v[64:67]
	v_mfma_f32_16x16x32_bf16 v[116:119], v[148:151], v[176:179], v[116:119]
	v_mfma_f32_16x16x32_bf16 v[112:115], v[168:171], v[176:179], v[112:115]
	v_mfma_f32_16x16x32_bf16 v[100:103], v[148:151], v[196:199], v[100:103]
	v_mfma_f32_16x16x32_bf16 v[96:99], v[168:171], v[196:199], v[96:99]
	v_mfma_f32_16x16x32_bf16 v[84:87], v[148:151], v[208:211], v[84:87]
	v_mfma_f32_16x16x32_bf16 v[80:83], v[168:171], v[208:211], v[80:83]
	v_mfma_f32_16x16x32_bf16 v[68:71], v[148:151], v[216:219], v[68:71]
	v_mfma_f32_16x16x32_bf16 v[64:67], v[168:171], v[216:219], v[64:67]
	s_barrier
; #define PG8_STAGE(bufoff, gbase, voff) do { _Pragma("unroll") for (int _i = 0; _i < 2; ++_i) \
;         __builtin_amdgcn_global_load_lds((const unsigned*)((const char*)(gbase) + (voff)[_i]), (LAS unsigned*)(lds + (bufoff) + ldsw + _i * 8192), 16, 0, 0); } while (0)
; #define PG8_LDA(dst, b, h) do { _Pragma("unroll") for (int m = 0; m < 4; ++m) _Pragma("unroll") for (int k = 0; k < 2; ++k) dst[m][k] = *(const LAS bf16x8*)(lds + PG8_SA(b, h) + aoff + m * 2048 + k * 1024); } while (0)
; #define PG8_MMA(ai, bj, At, Bt) do { __builtin_amdgcn_s_setprio(1); _Pragma("unroll") for (int m = 0; m < 4; ++m) _Pragma("unroll") for (int n = 0; n < 2; ++n) _Pragma("unroll") for (int k = 0; k < 2; ++k) \
;         acc[ai][bj][m][n] = __builtin_amdgcn_mfma_f32_16x16x32_bf16(Bt[n][k], At[m][k], acc[ai][bj][m][n], 0, 0, 0); __builtin_amdgcn_s_setprio(0); } while (0)
; #define PG8_WAIT_V(n) asm volatile("s_waitcnt vmcnt(" #n ")" ::: "memory")
; #define PG8_WAIT_L(n) asm volatile("s_waitcnt lgkmcnt(" #n ")" ::: "memory")
; #define PG8_BAR __builtin_amdgcn_s_barrier()
; #define PG8_SCHED __builtin_amdgcn_sched_barrier(0)
; template <class Epi, class Sched, bool ALIGN_EPI = true>
; __device__ __forceinline__ void gemm_phase(LAS unsigned char* lds, const Gemm g, const Sched& S, const Epi& E) {
;     ...
;             PG8_LDA(At, 1, 1); PG8_STAGE(PG8_SB(1, 0), b3, voffB); PG8_STAGE(PG8_SB(1, 1), b3 + hstep, voffB); PG8_STAGE(PG8_SA(1, 0), a3, voffA);
;             PG8_WAIT_V(8); PG8_WAIT_L(0); PG8_BAR; PG8_MMA(1, 0, At, B0); PG8_MMA(1, 1, At, B1); PG8_BAR; PG8_SCHED;
;         }
	s_add_i32 s22, s46, s35
	v_lshl_add_u64 v[180:181], v[180:181], 0, s[14:15]
	s_mov_b32 m0, s22
	ds_read_b128 v[172:175], v189 offset:49152
	ds_read_b128 v[176:179], v189 offset:50176
	ds_read_b128 v[192:195], v189 offset:51200
	ds_read_b128 v[196:199], v189 offset:52224
	ds_read_b128 v[204:207], v189 offset:53248
	ds_read_b128 v[208:211], v189 offset:54272
	ds_read_b128 v[212:215], v189 offset:55296
	ds_read_b128 v[216:219], v189 offset:56320
	global_load_lds_dwordx4 v[180:181], off
	s_add_i32 m0, s22, 0x2000
	s_add_u32 s22, s26, 0x160080
	v_lshl_add_u64 v[180:181], v[200:201], 0, s[14:15]
	s_addc_u32 s23, s27, 0
	s_add_i32 s26, s47, s35
	global_load_lds_dwordx4 v[180:181], off
	s_mov_b32 m0, s26
	v_lshl_add_u64 v[180:181], s[22:23], 0, v[154:155]
	global_load_lds_dwordx4 v[180:181], off
	s_add_i32 m0, s26, 0x2000
	v_lshl_add_u64 v[180:181], s[22:23], 0, v[158:159]
	global_load_lds_dwordx4 v[180:181], off
	s_mov_b32 m0, s40
	v_lshl_add_u64 v[180:181], v[202:203], 0, s[14:15]
	global_load_lds_dwordx4 v[180:181], off
	s_mov_b32 m0, s41
	v_lshl_add_u64 v[180:181], v[220:221], 0, s[14:15]
	global_load_lds_dwordx4 v[180:181], off
	s_waitcnt vmcnt(8)
	s_waitcnt lgkmcnt(0)
	s_barrier
	s_waitcnt lgkmcnt(0)
	v_mfma_f32_16x16x32_bf16 v[60:63], v[128:131], v[172:175], v[60:63]
	v_mfma_f32_16x16x32_bf16 v[56:59], v[136:139], v[172:175], v[56:59]
	v_mfma_f32_16x16x32_bf16 v[44:47], v[128:131], v[192:195], v[44:47]
	v_mfma_f32_16x16x32_bf16 v[40:43], v[136:139], v[192:195], v[40:43]
	v_mfma_f32_16x16x32_bf16 v[28:31], v[128:131], v[204:207], v[28:31]
	v_mfma_f32_16x16x32_bf16 v[24:27], v[136:139], v[204:207], v[24:27]
	v_mfma_f32_16x16x32_bf16 v[12:15], v[128:131], v[212:215], v[12:15]
	v_mfma_f32_16x16x32_bf16 v[8:11], v[136:139], v[212:215], v[8:11]
	v_mfma_f32_16x16x32_bf16 v[60:63], v[132:135], v[176:179], v[60:63]
	v_mfma_f32_16x16x32_bf16 v[56:59], v[140:143], v[176:179], v[56:59]
	v_mfma_f32_16x16x32_bf16 v[44:47], v[132:135], v[196:199], v[44:47]
	v_mfma_f32_16x16x32_bf16 v[40:43], v[140:143], v[196:199], v[40:43]
	v_mfma_f32_16x16x32_bf16 v[28:31], v[132:135], v[208:211], v[28:31]
	v_mfma_f32_16x16x32_bf16 v[24:27], v[140:143], v[208:211], v[24:27]
	v_mfma_f32_16x16x32_bf16 v[12:15], v[132:135], v[216:219], v[12:15]
	v_mfma_f32_16x16x32_bf16 v[8:11], v[140:143], v[216:219], v[8:11]
	v_mfma_f32_16x16x32_bf16 v[52:55], v[144:147], v[172:175], v[52:55]
	v_mfma_f32_16x16x32_bf16 v[48:51], v[164:167], v[172:175], v[48:51]
	v_mfma_f32_16x16x32_bf16 v[36:39], v[144:147], v[192:195], v[36:39]
	v_mfma_f32_16x16x32_bf16 v[32:35], v[164:167], v[192:195], v[32:35]
	v_mfma_f32_16x16x32_bf16 v[20:23], v[144:147], v[204:207], v[20:23]
	v_mfma_f32_16x16x32_bf16 v[16:19], v[164:167], v[204:207], v[16:19]
	v_mfma_f32_16x16x32_bf16 v[4:7], v[144:147], v[212:215], v[4:7]
	v_mfma_f32_16x16x32_bf16 v[0:3], v[164:167], v[212:215], v[0:3]
	v_mfma_f32_16x16x32_bf16 v[52:55], v[148:151], v[176:179], v[52:55]
	v_mfma_f32_16x16x32_bf16 v[48:51], v[168:171], v[176:179], v[48:51]
	v_mfma_f32_16x16x32_bf16 v[36:39], v[148:151], v[196:199], v[36:39]
	v_mfma_f32_16x16x32_bf16 v[32:35], v[168:171], v[196:199], v[32:35]
	v_mfma_f32_16x16x32_bf16 v[20:23], v[148:151], v[208:211], v[20:23]
	v_mfma_f32_16x16x32_bf16 v[16:19], v[168:171], v[208:211], v[16:19]
	v_mfma_f32_16x16x32_bf16 v[4:7], v[148:151], v[216:219], v[4:7]
	v_mfma_f32_16x16x32_bf16 v[0:3], v[168:171], v[216:219], v[0:3]
	s_add_i32 s56, s56, 2
	s_add_u32 s54, s54, 0x100
	s_addc_u32 s55, s55, 0
	s_cmpk_gt_u32 s56, 0x55
	s_mov_b64 s[22:23], s[24:25]
	s_barrier
	s_cbranch_scc0 .LBB0_746
	s_and_b64 vcc, exec, s[16:17]
	s_cbranch_vccz .LBB0_749
	s_barrier

; #define PG8_STAGE(bufoff, gbase, voff) do { _Pragma("unroll") for (int _i = 0; _i < 2; ++_i) \
;         __builtin_amdgcn_global_load_lds((const unsigned*)((const char*)(gbase) + (voff)[_i]), (LAS unsigned*)(lds + (bufoff) + ldsw + _i * 8192), 16, 0, 0); } while (0)
; #define PG8_LDA(dst, b, h) do { _Pragma("unroll") for (int m = 0; m < 4; ++m) _Pragma("unroll") for (int k = 0; k < 2; ++k) dst[m][k] = *(const LAS bf16x8*)(lds + PG8_SA(b, h) + aoff + m * 2048 + k * 1024); } while (0)
; #define PG8_LDB(dst, b, h) do { _Pragma("unroll") for (int n = 0; n < 2; ++n) _Pragma("unroll") for (int k = 0; k < 2; ++k) dst[n][k] = *(const LAS bf16x8*)(lds + PG8_SB(b, h) + boff + n * 2048 + k * 1024); } while (0)
; #define PG8_MMA(ai, bj, At, Bt) do { __builtin_amdgcn_s_setprio(1); _Pragma("unroll") for (int m = 0; m < 4; ++m) _Pragma("unroll") for (int n = 0; n < 2; ++n) _Pragma("unroll") for (int k = 0; k < 2; ++k) \
;         acc[ai][bj][m][n] = __builtin_amdgcn_mfma_f32_16x16x32_bf16(Bt[n][k], At[m][k], acc[ai][bj][m][n], 0, 0, 0); __builtin_amdgcn_s_setprio(0); } while (0)
; #define PG8_WAIT_V(n) asm volatile("s_waitcnt vmcnt(" #n ")" ::: "memory")
; #define PG8_WAIT_L(n) asm volatile("s_waitcnt lgkmcnt(" #n ")" ::: "memory")
; #define PG8_BAR __builtin_amdgcn_s_barrier()
; #define PG8_SCHED __builtin_amdgcn_sched_barrier(0)
; template <class Epi, class Sched, bool ALIGN_EPI = true>
; __device__ __forceinline__ void gemm_phase(LAS unsigned char* lds, const Gemm g, const Sched& S, const Epi& E) {
;     ...
;             const char* a1 = cA + (size_t)(t + 1) * kstep;
;             const char* a2 = last ? nA : cA + (size_t)(t + 2) * kstep; const char* b2 = last ? nB : cB + (size_t)(t + 2) * kstep;
;             const char* a3 = a2 + kstep; const char* b3 = b2 + kstep;
;             PG8_LDB(B0, 0, 0); PG8_LDB(B1, 0, 1); PG8_SCHED; PG8_LDA(At, 0, 0); PG8_STAGE(PG8_SA(1, 1), a1 + hstep, voffA);
;             PG8_WAIT_V(8); PG8_WAIT_L(0); PG8_BAR; PG8_MMA(0, 0, At, B0); PG8_MMA(0, 1, At, B1); PG8_BAR; PG8_SCHED;
;             PG8_LDA(At, 0, 1); PG8_STAGE(PG8_SB(0, 0), b2, voffB); PG8_STAGE(PG8_SB(0, 1), b2 + hstep, voffB); PG8_STAGE(PG8_SA(0, 0), a2, voffA);
.LBB0_837:
	ds_read_b128 v[120:123], v208
	ds_read_b128 v[124:127], v208 offset:1024
	ds_read_b128 v[132:135], v208 offset:2048
	ds_read_b128 v[136:139], v208 offset:3072
	ds_read_b128 v[144:147], v209
	ds_read_b128 v[148:151], v209 offset:1024
	ds_read_b128 v[152:155], v209 offset:2048
	ds_read_b128 v[156:159], v209 offset:3072
	s_add_u32 s36, s34, 0xfff80080
	s_addc_u32 s37, s35, -1
	s_cmp_eq_u32 s60, 28
	s_cselect_b32 s39, s55, s37
	s_cselect_b32 s38, s56, s36
	s_cselect_b32 s37, s11, s59
	s_cselect_b32 s36, s57, s58
	v_lshl_add_u64 v[200:201], s[34:35], 0, v[184:185]
	s_add_i32 m0, s42, 0xc000
	ds_read_b128 v[160:163], v210
	ds_read_b128 v[164:167], v210 offset:1024
	ds_read_b128 v[168:171], v210 offset:2048
	ds_read_b128 v[172:175], v210 offset:3072
	ds_read_b128 v[188:191], v210 offset:4096
	ds_read_b128 v[192:195], v210 offset:5120
	ds_read_b128 v[196:199], v210 offset:6144
	ds_read_b128 v[214:217], v210 offset:7168
	global_load_lds_dwordx4 v[200:201], off
	s_add_i32 m0, s42, 0xe000
	v_lshl_add_u64 v[200:201], s[34:35], 0, v[186:187]
	global_load_lds_dwordx4 v[200:201], off
	s_waitcnt vmcnt(8)
	s_waitcnt lgkmcnt(0)
	s_barrier
	s_waitcnt lgkmcnt(0)
	v_mfma_f32_16x16x32_bf16 v[140:143], v[120:123], v[160:163], v[140:143]
	v_mfma_f32_16x16x32_bf16 v[128:131], v[132:135], v[160:163], v[128:131]
	v_mfma_f32_16x16x32_bf16 v[108:111], v[120:123], v[168:171], v[108:111]
	v_mfma_f32_16x16x32_bf16 v[104:107], v[132:135], v[168:171], v[104:107]
	v_mfma_f32_16x16x32_bf16 v[92:95], v[120:123], v[188:191], v[92:95]
	v_mfma_f32_16x16x32_bf16 v[88:91], v[132:135], v[188:191], v[88:91]
	v_mfma_f32_16x16x32_bf16 v[76:79], v[120:123], v[196:199], v[76:79]
	v_mfma_f32_16x16x32_bf16 v[72:75], v[132:135], v[196:199], v[72:75]
	v_mfma_f32_16x16x32_bf16 v[140:143], v[124:127], v[164:167], v[140:143]
	v_mfma_f32_16x16x32_bf16 v[128:131], v[136:139], v[164:167], v[128:131]
	v_mfma_f32_16x16x32_bf16 v[108:111], v[124:127], v[172:175], v[108:111]
	v_mfma_f32_16x16x32_bf16 v[104:107], v[136:139], v[172:175], v[104:107]
	v_mfma_f32_16x16x32_bf16 v[92:95], v[124:127], v[192:195], v[92:95]
	v_mfma_f32_16x16x32_bf16 v[88:91], v[136:139], v[192:195], v[88:91]
	v_mfma_f32_16x16x32_bf16 v[76:79], v[124:127], v[214:217], v[76:79]
	v_mfma_f32_16x16x32_bf16 v[72:75], v[136:139], v[214:217], v[72:75]
	v_mfma_f32_16x16x32_bf16 v[116:119], v[144:147], v[160:163], v[116:119]
	v_mfma_f32_16x16x32_bf16 v[112:115], v[152:155], v[160:163], v[112:115]
	v_mfma_f32_16x16x32_bf16 v[100:103], v[144:147], v[168:171], v[100:103]
	v_mfma_f32_16x16x32_bf16 v[96:99], v[152:155], v[168:171], v[96:99]
	v_mfma_f32_16x16x32_bf16 v[84:87], v[144:147], v[188:191], v[84:87]
	v_mfma_f32_16x16x32_bf16 v[80:83], v[152:155], v[188:191], v[80:83]
	v_mfma_f32_16x16x32_bf16 v[68:71], v[144:147], v[196:199], v[68:71]
	v_mfma_f32_16x16x32_bf16 v[64:67], v[152:155], v[196:199], v[64:67]
	v_mfma_f32_16x16x32_bf16 v[116:119], v[148:151], v[164:167], v[116:119]
	v_mfma_f32_16x16x32_bf16 v[112:115], v[156:159], v[164:167], v[112:115]
	v_mfma_f32_16x16x32_bf16 v[100:103], v[148:151], v[172:175], v[100:103]
	v_mfma_f32_16x16x32_bf16 v[96:99], v[156:159], v[172:175], v[96:99]
	v_mfma_f32_16x16x32_bf16 v[84:87], v[148:151], v[192:195], v[84:87]
	v_mfma_f32_16x16x32_bf16 v[80:83], v[156:159], v[192:195], v[80:83]
	v_mfma_f32_16x16x32_bf16 v[68:71], v[148:151], v[214:217], v[68:71]
	v_mfma_f32_16x16x32_bf16 v[64:67], v[156:159], v[214:217], v[64:67]
	s_barrier
	s_add_i32 s46, s50, s41
	v_lshl_add_u64 v[200:201], s[36:37], 0, v[178:179]
	s_mov_b32 m0, s46
	ds_read_b128 v[160:163], v210 offset:16384
	ds_read_b128 v[164:167], v210 offset:17408
	ds_read_b128 v[168:171], v210 offset:18432
	ds_read_b128 v[172:175], v210 offset:19456
	ds_read_b128 v[188:191], v210 offset:20480
	ds_read_b128 v[192:195], v210 offset:21504
	ds_read_b128 v[196:199], v210 offset:22528
	ds_read_b128 v[214:217], v210 offset:23552
	global_load_lds_dwordx4 v[200:201], off
	s_add_i32 m0, s46, 0x2000
	s_add_u32 s46, s36, 0x80000
	v_lshl_add_u64 v[218:219], s[36:37], 0, v[182:183]
	s_addc_u32 s47, s37, 0
	s_add_i32 s61, s51, s41
	global_load_lds_dwordx4 v[218:219], off
	v_lshl_add_u64 v[220:221], s[46:47], 0, v[178:179]
	s_mov_b32 m0, s61
	v_lshl_add_u64 v[222:223], s[38:39], 0, v[180:181]
	global_load_lds_dwordx4 v[220:221], off
	s_add_i32 m0, s61, 0x2000
	v_lshl_add_u64 v[220:221], s[46:47], 0, v[182:183]
	global_load_lds_dwordx4 v[220:221], off
	s_mov_b32 m0, s42
	v_lshl_add_u64 v[220:221], s[38:39], 0, v[176:177]
	global_load_lds_dwordx4 v[220:221], off
	s_mov_b32 m0, s43
	s_nop 0
	global_load_lds_dwordx4 v[222:223], off
	s_waitcnt vmcnt(8)
	s_waitcnt lgkmcnt(0)
	s_barrier
; #define PG8_STAGE(bufoff, gbase, voff) do { _Pragma("unroll") for (int _i = 0; _i < 2; ++_i) \
;         __builtin_amdgcn_global_load_lds((const unsigned*)((const char*)(gbase) + (voff)[_i]), (LAS unsigned*)(lds + (bufoff) + ldsw + _i * 8192), 16, 0, 0); } while (0)
; #define PG8_LDA(dst, b, h) do { _Pragma("unroll") for (int m = 0; m < 4; ++m) _Pragma("unroll") for (int k = 0; k < 2; ++k) dst[m][k] = *(const LAS bf16x8*)(lds + PG8_SA(b, h) + aoff + m * 2048 + k * 1024); } while (0)
; #define PG8_LDB(dst, b, h) do { _Pragma("unroll") for (int n = 0; n < 2; ++n) _Pragma("unroll") for (int k = 0; k < 2; ++k) dst[n][k] = *(const LAS bf16x8*)(lds + PG8_SB(b, h) + boff + n * 2048 + k * 1024); } while (0)
; #define PG8_MMA(ai, bj, At, Bt) do { __builtin_amdgcn_s_setprio(1); _Pragma("unroll") for (int m = 0; m < 4; ++m) _Pragma("unroll") for (int n = 0; n < 2; ++n) _Pragma("unroll") for (int k = 0; k < 2; ++k) \
;         acc[ai][bj][m][n] = __builtin_amdgcn_mfma_f32_16x16x32_bf16(Bt[n][k], At[m][k], acc[ai][bj][m][n], 0, 0, 0); __builtin_amdgcn_s_setprio(0); } while (0)
; #define PG8_WAIT_V(n) asm volatile("s_waitcnt vmcnt(" #n ")" ::: "memory")
; #define PG8_WAIT_L(n) asm volatile("s_waitcnt lgkmcnt(" #n ")" ::: "memory")
; #define PG8_BAR __builtin_amdgcn_s_barrier()
; #define PG8_SCHED __builtin_amdgcn_sched_barrier(0)
; template <class Epi, class Sched, bool ALIGN_EPI = true>
; __device__ __forceinline__ void gemm_phase(LAS unsigned char* lds, const Gemm g, const Sched& S, const Epi& E) {
;     ...
;             PG8_WAIT_V(8); PG8_WAIT_L(0); PG8_BAR; PG8_MMA(1, 0, At, B0); PG8_MMA(1, 1, At, B1); PG8_BAR; PG8_SCHED;
;             PG8_LDB(B0, 1, 0); PG8_LDB(B1, 1, 1); PG8_SCHED; PG8_LDA(At, 1, 0); PG8_STAGE(PG8_SA(0, 1), a2 + hstep, voffA);
;             PG8_WAIT_V(8); PG8_WAIT_L(0); PG8_BAR; PG8_MMA(0, 0, At, B0); PG8_MMA(0, 1, At, B1); PG8_BAR; PG8_SCHED;
;             PG8_LDA(At, 1, 1); PG8_STAGE(PG8_SB(1, 0), b3, voffB); PG8_STAGE(PG8_SB(1, 1), b3 + hstep, voffB); PG8_STAGE(PG8_SA(1, 0), a3, voffA);
	s_waitcnt lgkmcnt(0)
	v_mfma_f32_16x16x32_bf16 v[60:63], v[120:123], v[160:163], v[60:63]
	v_mfma_f32_16x16x32_bf16 v[56:59], v[132:135], v[160:163], v[56:59]
	v_mfma_f32_16x16x32_bf16 v[44:47], v[120:123], v[168:171], v[44:47]
	v_mfma_f32_16x16x32_bf16 v[40:43], v[132:135], v[168:171], v[40:43]
	v_mfma_f32_16x16x32_bf16 v[28:31], v[120:123], v[188:191], v[28:31]
	v_mfma_f32_16x16x32_bf16 v[24:27], v[132:135], v[188:191], v[24:27]
	v_mfma_f32_16x16x32_bf16 v[12:15], v[120:123], v[196:199], v[12:15]
	v_mfma_f32_16x16x32_bf16 v[8:11], v[132:135], v[196:199], v[8:11]
	v_mfma_f32_16x16x32_bf16 v[60:63], v[124:127], v[164:167], v[60:63]
	v_mfma_f32_16x16x32_bf16 v[56:59], v[136:139], v[164:167], v[56:59]
	v_mfma_f32_16x16x32_bf16 v[44:47], v[124:127], v[172:175], v[44:47]
	v_mfma_f32_16x16x32_bf16 v[40:43], v[136:139], v[172:175], v[40:43]
	v_mfma_f32_16x16x32_bf16 v[28:31], v[124:127], v[192:195], v[28:31]
	v_mfma_f32_16x16x32_bf16 v[24:27], v[136:139], v[192:195], v[24:27]
	v_mfma_f32_16x16x32_bf16 v[12:15], v[124:127], v[214:217], v[12:15]
	v_mfma_f32_16x16x32_bf16 v[8:11], v[136:139], v[214:217], v[8:11]
	v_mfma_f32_16x16x32_bf16 v[52:55], v[144:147], v[160:163], v[52:55]
	v_mfma_f32_16x16x32_bf16 v[48:51], v[152:155], v[160:163], v[48:51]
	v_mfma_f32_16x16x32_bf16 v[36:39], v[144:147], v[168:171], v[36:39]
	v_mfma_f32_16x16x32_bf16 v[32:35], v[152:155], v[168:171], v[32:35]
	v_mfma_f32_16x16x32_bf16 v[20:23], v[144:147], v[188:191], v[20:23]
	v_mfma_f32_16x16x32_bf16 v[16:19], v[152:155], v[188:191], v[16:19]
	v_mfma_f32_16x16x32_bf16 v[4:7], v[144:147], v[196:199], v[4:7]
	v_mfma_f32_16x16x32_bf16 v[0:3], v[152:155], v[196:199], v[0:3]
	v_mfma_f32_16x16x32_bf16 v[52:55], v[148:151], v[164:167], v[52:55]
	v_mfma_f32_16x16x32_bf16 v[48:51], v[156:159], v[164:167], v[48:51]
	v_mfma_f32_16x16x32_bf16 v[36:39], v[148:151], v[172:175], v[36:39]
	v_mfma_f32_16x16x32_bf16 v[32:35], v[156:159], v[172:175], v[32:35]
	v_mfma_f32_16x16x32_bf16 v[20:23], v[148:151], v[192:195], v[20:23]
	v_mfma_f32_16x16x32_bf16 v[16:19], v[156:159], v[192:195], v[16:19]
	v_mfma_f32_16x16x32_bf16 v[4:7], v[148:151], v[214:217], v[4:7]
	v_mfma_f32_16x16x32_bf16 v[0:3], v[156:159], v[214:217], v[0:3]
	s_barrier
	s_add_i32 s46, 0, 0x18000
	s_add_i32 s47, 0, 0x1c000
	v_add_u32_e32 v136, s46, v206
	v_add_u32_e32 v156, s47, v206
	ds_read_b128 v[120:123], v136
	ds_read_b128 v[124:127], v136 offset:1024
	ds_read_b128 v[132:135], v136 offset:2048
	ds_read_b128 v[136:139], v136 offset:3072
	ds_read_b128 v[144:147], v156
	ds_read_b128 v[148:151], v156 offset:1024
	ds_read_b128 v[152:155], v156 offset:2048
	ds_read_b128 v[156:159], v156 offset:3072
	s_add_u32 s38, s38, 0x80000
	s_addc_u32 s39, s39, 0
	s_mov_b32 m0, s44
	v_lshl_add_u64 v[224:225], s[38:39], 0, v[176:177]
	ds_read_b128 v[160:163], v210 offset:32768
	ds_read_b128 v[164:167], v210 offset:33792
	ds_read_b128 v[168:171], v210 offset:34816
	ds_read_b128 v[172:175], v210 offset:35840
	ds_read_b128 v[188:191], v210 offset:36864
	ds_read_b128 v[192:195], v210 offset:37888
	ds_read_b128 v[196:199], v210 offset:38912
	ds_read_b128 v[214:217], v210 offset:39936
	global_load_lds_dwordx4 v[224:225], off
	s_mov_b32 m0, s45
	v_lshl_add_u64 v[224:225], s[38:39], 0, v[180:181]
	global_load_lds_dwordx4 v[224:225], off
	s_waitcnt vmcnt(8)
	s_waitcnt lgkmcnt(0)
	s_barrier
	s_waitcnt lgkmcnt(0)
	v_mfma_f32_16x16x32_bf16 v[140:143], v[120:123], v[160:163], v[140:143]
	v_mfma_f32_16x16x32_bf16 v[128:131], v[132:135], v[160:163], v[128:131]
	v_mfma_f32_16x16x32_bf16 v[108:111], v[120:123], v[168:171], v[108:111]
	v_mfma_f32_16x16x32_bf16 v[104:107], v[132:135], v[168:171], v[104:107]
	v_mfma_f32_16x16x32_bf16 v[92:95], v[120:123], v[188:191], v[92:95]
	v_mfma_f32_16x16x32_bf16 v[88:91], v[132:135], v[188:191], v[88:91]
	v_mfma_f32_16x16x32_bf16 v[76:79], v[120:123], v[196:199], v[76:79]
	v_mfma_f32_16x16x32_bf16 v[72:75], v[132:135], v[196:199], v[72:75]
	v_mfma_f32_16x16x32_bf16 v[140:143], v[124:127], v[164:167], v[140:143]
	v_mfma_f32_16x16x32_bf16 v[128:131], v[136:139], v[164:167], v[128:131]
	v_mfma_f32_16x16x32_bf16 v[108:111], v[124:127], v[172:175], v[108:111]
	v_mfma_f32_16x16x32_bf16 v[104:107], v[136:139], v[172:175], v[104:107]
	v_mfma_f32_16x16x32_bf16 v[92:95], v[124:127], v[192:195], v[92:95]
	v_mfma_f32_16x16x32_bf16 v[88:91], v[136:139], v[192:195], v[88:91]
	v_mfma_f32_16x16x32_bf16 v[76:79], v[124:127], v[214:217], v[76:79]
	v_mfma_f32_16x16x32_bf16 v[72:75], v[136:139], v[214:217], v[72:75]
	v_mfma_f32_16x16x32_bf16 v[116:119], v[144:147], v[160:163], v[116:119]
	v_mfma_f32_16x16x32_bf16 v[112:115], v[152:155], v[160:163], v[112:115]
	v_mfma_f32_16x16x32_bf16 v[100:103], v[144:147], v[168:171], v[100:103]
	v_mfma_f32_16x16x32_bf16 v[96:99], v[152:155], v[168:171], v[96:99]
	v_mfma_f32_16x16x32_bf16 v[84:87], v[144:147], v[188:191], v[84:87]
	v_mfma_f32_16x16x32_bf16 v[80:83], v[152:155], v[188:191], v[80:83]
	v_mfma_f32_16x16x32_bf16 v[68:71], v[144:147], v[196:199], v[68:71]
	v_mfma_f32_16x16x32_bf16 v[64:67], v[152:155], v[196:199], v[64:67]
	v_mfma_f32_16x16x32_bf16 v[116:119], v[148:151], v[164:167], v[116:119]
	v_mfma_f32_16x16x32_bf16 v[112:115], v[156:159], v[164:167], v[112:115]
	v_mfma_f32_16x16x32_bf16 v[100:103], v[148:151], v[172:175], v[100:103]
	v_mfma_f32_16x16x32_bf16 v[96:99], v[156:159], v[172:175], v[96:99]
	v_mfma_f32_16x16x32_bf16 v[84:87], v[148:151], v[192:195], v[84:87]
	v_mfma_f32_16x16x32_bf16 v[80:83], v[156:159], v[192:195], v[80:83]
	v_mfma_f32_16x16x32_bf16 v[68:71], v[148:151], v[214:217], v[68:71]
	v_mfma_f32_16x16x32_bf16 v[64:67], v[156:159], v[214:217], v[64:67]
	s_barrier
; #define PG8_STAGE(bufoff, gbase, voff) do { _Pragma("unroll") for (int _i = 0; _i < 2; ++_i) \
;         __builtin_amdgcn_global_load_lds((const unsigned*)((const char*)(gbase) + (voff)[_i]), (LAS unsigned*)(lds + (bufoff) + ldsw + _i * 8192), 16, 0, 0); } while (0)
; #define PG8_LDA(dst, b, h) do { _Pragma("unroll") for (int m = 0; m < 4; ++m) _Pragma("unroll") for (int k = 0; k < 2; ++k) dst[m][k] = *(const LAS bf16x8*)(lds + PG8_SA(b, h) + aoff + m * 2048 + k * 1024); } while (0)
; #define PG8_MMA(ai, bj, At, Bt) do { __builtin_amdgcn_s_setprio(1); _Pragma("unroll") for (int m = 0; m < 4; ++m) _Pragma("unroll") for (int n = 0; n < 2; ++n) _Pragma("unroll") for (int k = 0; k < 2; ++k) \
;         acc[ai][bj][m][n] = __builtin_amdgcn_mfma_f32_16x16x32_bf16(Bt[n][k], At[m][k], acc[ai][bj][m][n], 0, 0, 0); __builtin_amdgcn_s_setprio(0); } while (0)
; #define PG8_WAIT_V(n) asm volatile("s_waitcnt vmcnt(" #n ")" ::: "memory")
; #define PG8_WAIT_L(n) asm volatile("s_waitcnt lgkmcnt(" #n ")" ::: "memory")
; #define PG8_BAR __builtin_amdgcn_s_barrier()
; #define PG8_SCHED __builtin_amdgcn_sched_barrier(0)
; template <class Epi, class Sched, bool ALIGN_EPI = true>
; __device__ __forceinline__ void gemm_phase(LAS unsigned char* lds, const Gemm g, const Sched& S, const Epi& E) {
;     ...
;             PG8_LDA(At, 1, 1); PG8_STAGE(PG8_SB(1, 0), b3, voffB); PG8_STAGE(PG8_SB(1, 1), b3 + hstep, voffB); PG8_STAGE(PG8_SA(1, 0), a3, voffA);
;             PG8_WAIT_V(8); PG8_WAIT_L(0); PG8_BAR; PG8_MMA(1, 0, At, B0); PG8_MMA(1, 1, At, B1); PG8_BAR; PG8_SCHED;
;         }
	s_add_i32 s38, s46, s41
	v_lshl_add_u64 v[200:201], v[200:201], 0, s[26:27]
	s_mov_b32 m0, s38
	ds_read_b128 v[160:163], v210 offset:49152
	ds_read_b128 v[164:167], v210 offset:50176
	ds_read_b128 v[168:171], v210 offset:51200
	ds_read_b128 v[172:175], v210 offset:52224
	ds_read_b128 v[188:191], v210 offset:53248
	ds_read_b128 v[192:195], v210 offset:54272
	ds_read_b128 v[196:199], v210 offset:55296
	ds_read_b128 v[214:217], v210 offset:56320
	global_load_lds_dwordx4 v[200:201], off
	s_add_i32 m0, s38, 0x2000
	s_add_u32 s36, s36, 0x80080
	v_lshl_add_u64 v[200:201], v[218:219], 0, s[26:27]
	s_addc_u32 s37, s37, 0
	s_add_i32 s38, s47, s41
	global_load_lds_dwordx4 v[200:201], off
	s_mov_b32 m0, s38
	v_lshl_add_u64 v[200:201], s[36:37], 0, v[178:179]
	global_load_lds_dwordx4 v[200:201], off
	s_add_i32 m0, s38, 0x2000
	v_lshl_add_u64 v[200:201], s[36:37], 0, v[182:183]
	global_load_lds_dwordx4 v[200:201], off
	s_mov_b32 m0, s48
	v_lshl_add_u64 v[200:201], v[220:221], 0, s[26:27]
	global_load_lds_dwordx4 v[200:201], off
	s_mov_b32 m0, s49
	v_lshl_add_u64 v[200:201], v[222:223], 0, s[26:27]
	global_load_lds_dwordx4 v[200:201], off
	s_waitcnt vmcnt(8)
	s_waitcnt lgkmcnt(0)
	s_barrier
	s_waitcnt lgkmcnt(0)
	v_mfma_f32_16x16x32_bf16 v[60:63], v[120:123], v[160:163], v[60:63]
	v_mfma_f32_16x16x32_bf16 v[56:59], v[132:135], v[160:163], v[56:59]
	v_mfma_f32_16x16x32_bf16 v[44:47], v[120:123], v[168:171], v[44:47]
	v_mfma_f32_16x16x32_bf16 v[40:43], v[132:135], v[168:171], v[40:43]
	v_mfma_f32_16x16x32_bf16 v[28:31], v[120:123], v[188:191], v[28:31]
	v_mfma_f32_16x16x32_bf16 v[24:27], v[132:135], v[188:191], v[24:27]
	v_mfma_f32_16x16x32_bf16 v[12:15], v[120:123], v[196:199], v[12:15]
	v_mfma_f32_16x16x32_bf16 v[8:11], v[132:135], v[196:199], v[8:11]
	v_mfma_f32_16x16x32_bf16 v[60:63], v[124:127], v[164:167], v[60:63]
	v_mfma_f32_16x16x32_bf16 v[56:59], v[136:139], v[164:167], v[56:59]
	v_mfma_f32_16x16x32_bf16 v[44:47], v[124:127], v[172:175], v[44:47]
	v_mfma_f32_16x16x32_bf16 v[40:43], v[136:139], v[172:175], v[40:43]
	v_mfma_f32_16x16x32_bf16 v[28:31], v[124:127], v[192:195], v[28:31]
	v_mfma_f32_16x16x32_bf16 v[24:27], v[136:139], v[192:195], v[24:27]
	v_mfma_f32_16x16x32_bf16 v[12:15], v[124:127], v[214:217], v[12:15]
	v_mfma_f32_16x16x32_bf16 v[8:11], v[136:139], v[214:217], v[8:11]
	v_mfma_f32_16x16x32_bf16 v[52:55], v[144:147], v[160:163], v[52:55]
	v_mfma_f32_16x16x32_bf16 v[48:51], v[152:155], v[160:163], v[48:51]
	v_mfma_f32_16x16x32_bf16 v[36:39], v[144:147], v[168:171], v[36:39]
	v_mfma_f32_16x16x32_bf16 v[32:35], v[152:155], v[168:171], v[32:35]
	v_mfma_f32_16x16x32_bf16 v[20:23], v[144:147], v[188:191], v[20:23]
	v_mfma_f32_16x16x32_bf16 v[16:19], v[152:155], v[188:191], v[16:19]
	v_mfma_f32_16x16x32_bf16 v[4:7], v[144:147], v[196:199], v[4:7]
	v_mfma_f32_16x16x32_bf16 v[0:3], v[152:155], v[196:199], v[0:3]
	v_mfma_f32_16x16x32_bf16 v[52:55], v[148:151], v[164:167], v[52:55]
	v_mfma_f32_16x16x32_bf16 v[48:51], v[156:159], v[164:167], v[48:51]
	v_mfma_f32_16x16x32_bf16 v[36:39], v[148:151], v[172:175], v[36:39]
	v_mfma_f32_16x16x32_bf16 v[32:35], v[156:159], v[172:175], v[32:35]
	v_mfma_f32_16x16x32_bf16 v[20:23], v[148:151], v[192:195], v[20:23]
	v_mfma_f32_16x16x32_bf16 v[16:19], v[156:159], v[192:195], v[16:19]
	v_mfma_f32_16x16x32_bf16 v[4:7], v[148:151], v[214:217], v[4:7]
	v_mfma_f32_16x16x32_bf16 v[0:3], v[156:159], v[214:217], v[0:3]
	s_add_i32 s60, s60, 2
	s_add_u32 s34, s34, 0x100
	s_addc_u32 s35, s35, 0
	s_add_u32 s58, s58, 0x100
	s_addc_u32 s59, s59, 0
	s_cmp_gt_u32 s60, 29
	s_barrier
	s_cbranch_scc0 .LBB0_837
	s_and_b64 vcc, exec, s[28:29]
	s_cbranch_vccz .LBB0_840
	s_barrier
